# stack: P7 epilogue rewrite + saddr DMA + 4x8 tile order + half-rendezvous K-loop sync (prio2) for P7, P1 row-scale epilogue hoisted loads, sgu pass1 16 loads in flight
# speedup vs baseline: 1.0098x; 1.0098x over previous
.LBB0_251:
	v_lshl_add_u32 v132, s20, 8, v170
	v_ashrrev_i32_e32 v133, 31, v132
	v_lshlrev_b32_e32 v130, 1, v172
	v_lshl_add_u64 v[186:187], v[132:133], 2, s[68:69]
	global_load_dword v188, v[186:187], off
	global_load_dword v190, v[186:187], off offset:64
	global_load_dword v192, v[186:187], off offset:128
	global_load_dword v194, v[186:187], off offset:192
	global_load_dword v196, v[186:187], off offset:512
	global_load_dword v198, v[186:187], off offset:576
	global_load_dword v200, v[186:187], off offset:640
	global_load_dword v202, v[186:187], off offset:704
	v_lshl_or_b32 v152, s38, 9, v130
	v_lshlrev_b64 v[128:129], 12, v[132:133]
	v_lshl_add_u64 v[128:129], s[12:13], 0, v[128:129]
	v_lshl_add_u64 v[128:129], v[128:129], 0, v[152:153]
	s_mov_b32 s92, 0x10000
	s_mov_b32 s93, 0
	v_lshl_add_u64 v[168:169], v[128:129], 0, s[78:79]
	v_mov_b64_e32 v[178:179], v[128:129]
	s_waitcnt vmcnt(7)
	v_pk_mul_f32 v[124:125], v[124:125], v[188:189] op_sel_hi:[1,0]
	v_pk_mul_f32 v[126:127], v[126:127], v[188:189] op_sel_hi:[1,0]
	v_pk_mul_f32 v[120:121], v[120:121], v[188:189] op_sel_hi:[1,0]
	v_pk_mul_f32 v[122:123], v[122:123], v[188:189] op_sel_hi:[1,0]
	v_cvt_pk_bf16_f32 v208, v124, v125
	v_cvt_pk_bf16_f32 v209, v126, v127
	v_cvt_pk_bf16_f32 v210, v120, v121
	v_cvt_pk_bf16_f32 v211, v122, v123
	global_store_dwordx4 v[178:179], v[208:211], off
	v_pk_mul_f32 v[92:93], v[92:93], v[188:189] op_sel_hi:[1,0]
	v_pk_mul_f32 v[94:95], v[94:95], v[188:189] op_sel_hi:[1,0]
	v_pk_mul_f32 v[88:89], v[88:89], v[188:189] op_sel_hi:[1,0]
	v_pk_mul_f32 v[90:91], v[90:91], v[188:189] op_sel_hi:[1,0]
	v_cvt_pk_bf16_f32 v212, v92, v93
	v_cvt_pk_bf16_f32 v213, v94, v95
	v_cvt_pk_bf16_f32 v214, v88, v89
	v_cvt_pk_bf16_f32 v215, v90, v91
	global_store_dwordx4 v[178:179], v[212:215], off offset:256
	s_waitcnt vmcnt(8)
	v_lshl_add_u64 v[178:179], v[178:179], 0, s[92:93]
	v_pk_mul_f32 v[116:117], v[116:117], v[190:191] op_sel_hi:[1,0]
	v_pk_mul_f32 v[118:119], v[118:119], v[190:191] op_sel_hi:[1,0]
	v_pk_mul_f32 v[112:113], v[112:113], v[190:191] op_sel_hi:[1,0]
	v_pk_mul_f32 v[114:115], v[114:115], v[190:191] op_sel_hi:[1,0]
	v_cvt_pk_bf16_f32 v208, v116, v117
	v_cvt_pk_bf16_f32 v209, v118, v119
	v_cvt_pk_bf16_f32 v210, v112, v113
	v_cvt_pk_bf16_f32 v211, v114, v115
	global_store_dwordx4 v[178:179], v[208:211], off
	v_pk_mul_f32 v[84:85], v[84:85], v[190:191] op_sel_hi:[1,0]
	v_pk_mul_f32 v[86:87], v[86:87], v[190:191] op_sel_hi:[1,0]
	v_pk_mul_f32 v[80:81], v[80:81], v[190:191] op_sel_hi:[1,0]
	v_pk_mul_f32 v[82:83], v[82:83], v[190:191] op_sel_hi:[1,0]
	v_cvt_pk_bf16_f32 v212, v84, v85
	v_cvt_pk_bf16_f32 v213, v86, v87
	v_cvt_pk_bf16_f32 v214, v80, v81
	v_cvt_pk_bf16_f32 v215, v82, v83
	global_store_dwordx4 v[178:179], v[212:215], off offset:256
	s_waitcnt vmcnt(9)
	v_lshl_add_u64 v[178:179], v[178:179], 0, s[92:93]
	v_pk_mul_f32 v[108:109], v[108:109], v[192:193] op_sel_hi:[1,0]
	v_pk_mul_f32 v[110:111], v[110:111], v[192:193] op_sel_hi:[1,0]
	v_pk_mul_f32 v[104:105], v[104:105], v[192:193] op_sel_hi:[1,0]
	v_pk_mul_f32 v[106:107], v[106:107], v[192:193] op_sel_hi:[1,0]
	v_cvt_pk_bf16_f32 v208, v108, v109
	v_cvt_pk_bf16_f32 v209, v110, v111
	v_cvt_pk_bf16_f32 v210, v104, v105
	v_cvt_pk_bf16_f32 v211, v106, v107
	global_store_dwordx4 v[178:179], v[208:211], off
	v_pk_mul_f32 v[76:77], v[76:77], v[192:193] op_sel_hi:[1,0]
	v_pk_mul_f32 v[78:79], v[78:79], v[192:193] op_sel_hi:[1,0]
	v_pk_mul_f32 v[72:73], v[72:73], v[192:193] op_sel_hi:[1,0]
	v_pk_mul_f32 v[74:75], v[74:75], v[192:193] op_sel_hi:[1,0]
	v_cvt_pk_bf16_f32 v212, v76, v77
	v_cvt_pk_bf16_f32 v213, v78, v79
	v_cvt_pk_bf16_f32 v214, v72, v73
	v_cvt_pk_bf16_f32 v215, v74, v75
	global_store_dwordx4 v[178:179], v[212:215], off offset:256
	s_waitcnt vmcnt(10)
	v_lshl_add_u64 v[178:179], v[178:179], 0, s[92:93]
	v_pk_mul_f32 v[100:101], v[100:101], v[194:195] op_sel_hi:[1,0]
	v_pk_mul_f32 v[102:103], v[102:103], v[194:195] op_sel_hi:[1,0]
	v_pk_mul_f32 v[96:97], v[96:97], v[194:195] op_sel_hi:[1,0]
	v_pk_mul_f32 v[98:99], v[98:99], v[194:195] op_sel_hi:[1,0]
	v_cvt_pk_bf16_f32 v208, v100, v101
	v_cvt_pk_bf16_f32 v209, v102, v103
	v_cvt_pk_bf16_f32 v210, v96, v97
	v_cvt_pk_bf16_f32 v211, v98, v99
	global_store_dwordx4 v[178:179], v[208:211], off
	v_pk_mul_f32 v[68:69], v[68:69], v[194:195] op_sel_hi:[1,0]
	v_pk_mul_f32 v[70:71], v[70:71], v[194:195] op_sel_hi:[1,0]
	v_pk_mul_f32 v[64:65], v[64:65], v[194:195] op_sel_hi:[1,0]
	v_pk_mul_f32 v[66:67], v[66:67], v[194:195] op_sel_hi:[1,0]
	v_cvt_pk_bf16_f32 v212, v68, v69
	v_cvt_pk_bf16_f32 v213, v70, v71
	v_cvt_pk_bf16_f32 v214, v64, v65
	v_cvt_pk_bf16_f32 v215, v66, v67
	global_store_dwordx4 v[178:179], v[212:215], off offset:256
	s_waitcnt vmcnt(11)
	v_lshl_add_u64 v[180:181], v[128:129], 0, s[46:47]
	v_pk_mul_f32 v[60:61], v[60:61], v[196:197] op_sel_hi:[1,0]
	v_pk_mul_f32 v[62:63], v[62:63], v[196:197] op_sel_hi:[1,0]
	v_pk_mul_f32 v[56:57], v[56:57], v[196:197] op_sel_hi:[1,0]
	v_pk_mul_f32 v[58:59], v[58:59], v[196:197] op_sel_hi:[1,0]
	v_cvt_pk_bf16_f32 v208, v60, v61
	v_cvt_pk_bf16_f32 v209, v62, v63
	v_cvt_pk_bf16_f32 v210, v56, v57
	v_cvt_pk_bf16_f32 v211, v58, v59
	global_store_dwordx4 v[180:181], v[208:211], off
	v_pk_mul_f32 v[28:29], v[28:29], v[196:197] op_sel_hi:[1,0]
	v_pk_mul_f32 v[30:31], v[30:31], v[196:197] op_sel_hi:[1,0]
	v_pk_mul_f32 v[24:25], v[24:25], v[196:197] op_sel_hi:[1,0]
	v_pk_mul_f32 v[26:27], v[26:27], v[196:197] op_sel_hi:[1,0]
	v_cvt_pk_bf16_f32 v212, v28, v29
	v_cvt_pk_bf16_f32 v213, v30, v31
	v_cvt_pk_bf16_f32 v214, v24, v25
	v_cvt_pk_bf16_f32 v215, v26, v27
	global_store_dwordx4 v[180:181], v[212:215], off offset:256
	s_waitcnt vmcnt(12)
	v_lshl_add_u64 v[180:181], v[128:129], 0, s[74:75]
	v_pk_mul_f32 v[52:53], v[52:53], v[198:199] op_sel_hi:[1,0]
	v_pk_mul_f32 v[54:55], v[54:55], v[198:199] op_sel_hi:[1,0]
	v_pk_mul_f32 v[48:49], v[48:49], v[198:199] op_sel_hi:[1,0]
	v_pk_mul_f32 v[50:51], v[50:51], v[198:199] op_sel_hi:[1,0]
	v_cvt_pk_bf16_f32 v208, v52, v53
	v_cvt_pk_bf16_f32 v209, v54, v55
	v_cvt_pk_bf16_f32 v210, v48, v49
	v_cvt_pk_bf16_f32 v211, v50, v51
	global_store_dwordx4 v[180:181], v[208:211], off
	v_pk_mul_f32 v[20:21], v[20:21], v[198:199] op_sel_hi:[1,0]
	v_pk_mul_f32 v[22:23], v[22:23], v[198:199] op_sel_hi:[1,0]
	v_pk_mul_f32 v[16:17], v[16:17], v[198:199] op_sel_hi:[1,0]
	v_pk_mul_f32 v[18:19], v[18:19], v[198:199] op_sel_hi:[1,0]
	v_cvt_pk_bf16_f32 v212, v20, v21
	v_cvt_pk_bf16_f32 v213, v22, v23
	v_cvt_pk_bf16_f32 v214, v16, v17
	v_cvt_pk_bf16_f32 v215, v18, v19
	global_store_dwordx4 v[180:181], v[212:215], off offset:256
	s_waitcnt vmcnt(13)
	v_lshl_add_u64 v[180:181], v[128:129], 0, s[76:77]
	v_pk_mul_f32 v[44:45], v[44:45], v[200:201] op_sel_hi:[1,0]
	v_pk_mul_f32 v[46:47], v[46:47], v[200:201] op_sel_hi:[1,0]
	v_pk_mul_f32 v[40:41], v[40:41], v[200:201] op_sel_hi:[1,0]
	v_pk_mul_f32 v[42:43], v[42:43], v[200:201] op_sel_hi:[1,0]
	v_cvt_pk_bf16_f32 v208, v44, v45
	v_cvt_pk_bf16_f32 v209, v46, v47
	v_cvt_pk_bf16_f32 v210, v40, v41
	v_cvt_pk_bf16_f32 v211, v42, v43
	global_store_dwordx4 v[180:181], v[208:211], off
	v_pk_mul_f32 v[12:13], v[12:13], v[200:201] op_sel_hi:[1,0]
	v_pk_mul_f32 v[14:15], v[14:15], v[200:201] op_sel_hi:[1,0]
	v_pk_mul_f32 v[8:9], v[8:9], v[200:201] op_sel_hi:[1,0]
	v_pk_mul_f32 v[10:11], v[10:11], v[200:201] op_sel_hi:[1,0]
	v_cvt_pk_bf16_f32 v212, v12, v13
	v_cvt_pk_bf16_f32 v213, v14, v15
	v_cvt_pk_bf16_f32 v214, v8, v9
	v_cvt_pk_bf16_f32 v215, v10, v11
	global_store_dwordx4 v[180:181], v[212:215], off offset:256
	s_waitcnt vmcnt(14)
	v_pk_mul_f32 v[36:37], v[36:37], v[202:203] op_sel_hi:[1,0]
	v_pk_mul_f32 v[38:39], v[38:39], v[202:203] op_sel_hi:[1,0]
	v_pk_mul_f32 v[32:33], v[32:33], v[202:203] op_sel_hi:[1,0]
	v_pk_mul_f32 v[34:35], v[34:35], v[202:203] op_sel_hi:[1,0]
	v_cvt_pk_bf16_f32 v208, v36, v37
	v_cvt_pk_bf16_f32 v209, v38, v39
	v_cvt_pk_bf16_f32 v210, v32, v33
	v_cvt_pk_bf16_f32 v211, v34, v35
	global_store_dwordx4 v[168:169], v[208:211], off
	v_pk_mul_f32 v[134:135], v[6:7], v[202:203] op_sel_hi:[1,0]
	v_pk_mul_f32 v[128:129], v[0:1], v[202:203] op_sel_hi:[1,0]
	v_pk_mul_f32 v[132:133], v[4:5], v[202:203] op_sel_hi:[1,0]
	v_pk_mul_f32 v[130:131], v[2:3], v[202:203] op_sel_hi:[1,0]

.LBB0_390:
	v_lshl_add_u64 v[12:13], v[10:11], 0, s[42:43]
	s_mov_b32 s8, 0x100000
	s_mov_b32 s9, 0
	global_load_dwordx4 v[176:179], v[12:13], off
	v_lshl_add_u64 v[12:13], v[12:13], 0, s[8:9]
	global_load_dwordx4 v[180:183], v[12:13], off
	v_lshl_add_u64 v[12:13], v[12:13], 0, s[8:9]
	global_load_dwordx4 v[184:187], v[12:13], off
	v_lshl_add_u64 v[12:13], v[12:13], 0, s[8:9]
	global_load_dwordx4 v[188:191], v[12:13], off
	v_lshl_add_u64 v[12:13], v[12:13], 0, s[8:9]
	global_load_dwordx4 v[192:195], v[12:13], off
	v_lshl_add_u64 v[12:13], v[12:13], 0, s[8:9]
	global_load_dwordx4 v[196:199], v[12:13], off
	v_lshl_add_u64 v[12:13], v[12:13], 0, s[8:9]
	global_load_dwordx4 v[200:203], v[12:13], off
	v_lshl_add_u64 v[12:13], v[12:13], 0, s[8:9]
	global_load_dwordx4 v[204:207], v[12:13], off
	v_lshl_add_u64 v[12:13], v[12:13], 0, s[8:9]
	global_load_dwordx4 v[208:211], v[12:13], off
	v_lshl_add_u64 v[12:13], v[12:13], 0, s[8:9]
	global_load_dwordx4 v[212:215], v[12:13], off
	v_lshl_add_u64 v[12:13], v[12:13], 0, s[8:9]
	global_load_dwordx4 v[216:219], v[12:13], off
	v_lshl_add_u64 v[12:13], v[12:13], 0, s[8:9]
	global_load_dwordx4 v[220:223], v[12:13], off
	v_lshl_add_u64 v[12:13], v[12:13], 0, s[8:9]
	global_load_dwordx4 v[224:227], v[12:13], off
	v_lshl_add_u64 v[12:13], v[12:13], 0, s[8:9]
	global_load_dwordx4 v[228:231], v[12:13], off
	v_lshl_add_u64 v[12:13], v[12:13], 0, s[8:9]
	global_load_dwordx4 v[232:235], v[12:13], off
	v_lshl_add_u64 v[12:13], v[12:13], 0, s[8:9]
	global_load_dwordx4 v[236:239], v[12:13], off
	v_lshl_add_u64 v[12:13], v[12:13], 0, s[8:9]
	s_mov_b32 s8, 0x1000000
	v_lshl_add_u64 v[10:11], v[10:11], 0, s[8:9]
	s_add_u32 s46, s46, 1
	s_waitcnt vmcnt(15)
	v_lshlrev_b32_e32 v20, 16, v176
	v_and_b32_e32 v21, 0xffff0000, v176
	v_lshlrev_b32_e32 v22, 16, v177
	v_and_b32_e32 v23, 0xffff0000, v177
	v_lshlrev_b32_e32 v24, 16, v178
	v_and_b32_e32 v25, 0xffff0000, v178
	v_lshlrev_b32_e32 v26, 16, v179
	v_and_b32_e32 v27, 0xffff0000, v179
	v_pk_fma_f32 v[8:9], v[20:21], v[20:21], v[8:9]
	v_pk_fma_f32 v[6:7], v[22:23], v[22:23], v[6:7]
	v_pk_fma_f32 v[4:5], v[24:25], v[24:25], v[4:5]
	v_pk_fma_f32 v[2:3], v[26:27], v[26:27], v[2:3]
	s_waitcnt vmcnt(14)
	v_lshlrev_b32_e32 v20, 16, v180
	v_and_b32_e32 v21, 0xffff0000, v180
	v_lshlrev_b32_e32 v22, 16, v181
	v_and_b32_e32 v23, 0xffff0000, v181
	v_lshlrev_b32_e32 v24, 16, v182
	v_and_b32_e32 v25, 0xffff0000, v182
	v_lshlrev_b32_e32 v26, 16, v183
	v_and_b32_e32 v27, 0xffff0000, v183
	v_pk_fma_f32 v[8:9], v[20:21], v[20:21], v[8:9]
	v_pk_fma_f32 v[6:7], v[22:23], v[22:23], v[6:7]
	v_pk_fma_f32 v[4:5], v[24:25], v[24:25], v[4:5]
	v_pk_fma_f32 v[2:3], v[26:27], v[26:27], v[2:3]
	s_waitcnt vmcnt(13)
	v_lshlrev_b32_e32 v20, 16, v184
	v_and_b32_e32 v21, 0xffff0000, v184
	v_lshlrev_b32_e32 v22, 16, v185
	v_and_b32_e32 v23, 0xffff0000, v185
	v_lshlrev_b32_e32 v24, 16, v186
	v_and_b32_e32 v25, 0xffff0000, v186
	v_lshlrev_b32_e32 v26, 16, v187
	v_and_b32_e32 v27, 0xffff0000, v187
	v_pk_fma_f32 v[8:9], v[20:21], v[20:21], v[8:9]
	v_pk_fma_f32 v[6:7], v[22:23], v[22:23], v[6:7]
	v_pk_fma_f32 v[4:5], v[24:25], v[24:25], v[4:5]
	v_pk_fma_f32 v[2:3], v[26:27], v[26:27], v[2:3]
	s_waitcnt vmcnt(12)
	v_lshlrev_b32_e32 v20, 16, v188
	v_and_b32_e32 v21, 0xffff0000, v188
	v_lshlrev_b32_e32 v22, 16, v189
	v_and_b32_e32 v23, 0xffff0000, v189
	v_lshlrev_b32_e32 v24, 16, v190
	v_and_b32_e32 v25, 0xffff0000, v190
	v_lshlrev_b32_e32 v26, 16, v191
	v_and_b32_e32 v27, 0xffff0000, v191
	v_pk_fma_f32 v[8:9], v[20:21], v[20:21], v[8:9]
	v_pk_fma_f32 v[6:7], v[22:23], v[22:23], v[6:7]
	v_pk_fma_f32 v[4:5], v[24:25], v[24:25], v[4:5]
	v_pk_fma_f32 v[2:3], v[26:27], v[26:27], v[2:3]
	s_waitcnt vmcnt(11)
	v_lshlrev_b32_e32 v20, 16, v192
	v_and_b32_e32 v21, 0xffff0000, v192
	v_lshlrev_b32_e32 v22, 16, v193
	v_and_b32_e32 v23, 0xffff0000, v193
	v_lshlrev_b32_e32 v24, 16, v194
	v_and_b32_e32 v25, 0xffff0000, v194
	v_lshlrev_b32_e32 v26, 16, v195
	v_and_b32_e32 v27, 0xffff0000, v195
	v_pk_fma_f32 v[8:9], v[20:21], v[20:21], v[8:9]
	v_pk_fma_f32 v[6:7], v[22:23], v[22:23], v[6:7]
	v_pk_fma_f32 v[4:5], v[24:25], v[24:25], v[4:5]
	v_pk_fma_f32 v[2:3], v[26:27], v[26:27], v[2:3]
	s_waitcnt vmcnt(10)
	v_lshlrev_b32_e32 v20, 16, v196
	v_and_b32_e32 v21, 0xffff0000, v196
	v_lshlrev_b32_e32 v22, 16, v197
	v_and_b32_e32 v23, 0xffff0000, v197
	v_lshlrev_b32_e32 v24, 16, v198
	v_and_b32_e32 v25, 0xffff0000, v198
	v_lshlrev_b32_e32 v26, 16, v199
	v_and_b32_e32 v27, 0xffff0000, v199
	v_pk_fma_f32 v[8:9], v[20:21], v[20:21], v[8:9]
	v_pk_fma_f32 v[6:7], v[22:23], v[22:23], v[6:7]
	v_pk_fma_f32 v[4:5], v[24:25], v[24:25], v[4:5]
	v_pk_fma_f32 v[2:3], v[26:27], v[26:27], v[2:3]
	s_waitcnt vmcnt(9)
	v_lshlrev_b32_e32 v20, 16, v200
	v_and_b32_e32 v21, 0xffff0000, v200
	v_lshlrev_b32_e32 v22, 16, v201
	v_and_b32_e32 v23, 0xffff0000, v201
	v_lshlrev_b32_e32 v24, 16, v202
	v_and_b32_e32 v25, 0xffff0000, v202
	v_lshlrev_b32_e32 v26, 16, v203
	v_and_b32_e32 v27, 0xffff0000, v203
	v_pk_fma_f32 v[8:9], v[20:21], v[20:21], v[8:9]
	v_pk_fma_f32 v[6:7], v[22:23], v[22:23], v[6:7]
	v_pk_fma_f32 v[4:5], v[24:25], v[24:25], v[4:5]
	v_pk_fma_f32 v[2:3], v[26:27], v[26:27], v[2:3]
	s_waitcnt vmcnt(8)
	v_lshlrev_b32_e32 v20, 16, v204
	v_and_b32_e32 v21, 0xffff0000, v204
	v_lshlrev_b32_e32 v22, 16, v205
	v_and_b32_e32 v23, 0xffff0000, v205
	v_lshlrev_b32_e32 v24, 16, v206
	v_and_b32_e32 v25, 0xffff0000, v206
	v_lshlrev_b32_e32 v26, 16, v207
	v_and_b32_e32 v27, 0xffff0000, v207
	v_pk_fma_f32 v[8:9], v[20:21], v[20:21], v[8:9]
	v_pk_fma_f32 v[6:7], v[22:23], v[22:23], v[6:7]
	v_pk_fma_f32 v[4:5], v[24:25], v[24:25], v[4:5]
	v_pk_fma_f32 v[2:3], v[26:27], v[26:27], v[2:3]
	s_waitcnt vmcnt(7)
	v_lshlrev_b32_e32 v20, 16, v208
	v_and_b32_e32 v21, 0xffff0000, v208
	v_lshlrev_b32_e32 v22, 16, v209
	v_and_b32_e32 v23, 0xffff0000, v209
	v_lshlrev_b32_e32 v24, 16, v210
	v_and_b32_e32 v25, 0xffff0000, v210
	v_lshlrev_b32_e32 v26, 16, v211
	v_and_b32_e32 v27, 0xffff0000, v211
	v_pk_fma_f32 v[8:9], v[20:21], v[20:21], v[8:9]
	v_pk_fma_f32 v[6:7], v[22:23], v[22:23], v[6:7]
	v_pk_fma_f32 v[4:5], v[24:25], v[24:25], v[4:5]
	v_pk_fma_f32 v[2:3], v[26:27], v[26:27], v[2:3]
	s_waitcnt vmcnt(6)
	v_lshlrev_b32_e32 v20, 16, v212
	v_and_b32_e32 v21, 0xffff0000, v212
	v_lshlrev_b32_e32 v22, 16, v213
	v_and_b32_e32 v23, 0xffff0000, v213
	v_lshlrev_b32_e32 v24, 16, v214
	v_and_b32_e32 v25, 0xffff0000, v214
	v_lshlrev_b32_e32 v26, 16, v215
	v_and_b32_e32 v27, 0xffff0000, v215
	v_pk_fma_f32 v[8:9], v[20:21], v[20:21], v[8:9]
	v_pk_fma_f32 v[6:7], v[22:23], v[22:23], v[6:7]
	v_pk_fma_f32 v[4:5], v[24:25], v[24:25], v[4:5]
	v_pk_fma_f32 v[2:3], v[26:27], v[26:27], v[2:3]
	s_waitcnt vmcnt(5)
	v_lshlrev_b32_e32 v20, 16, v216
	v_and_b32_e32 v21, 0xffff0000, v216
	v_lshlrev_b32_e32 v22, 16, v217
	v_and_b32_e32 v23, 0xffff0000, v217
	v_lshlrev_b32_e32 v24, 16, v218
	v_and_b32_e32 v25, 0xffff0000, v218
	v_lshlrev_b32_e32 v26, 16, v219
	v_and_b32_e32 v27, 0xffff0000, v219
	v_pk_fma_f32 v[8:9], v[20:21], v[20:21], v[8:9]
	v_pk_fma_f32 v[6:7], v[22:23], v[22:23], v[6:7]
	v_pk_fma_f32 v[4:5], v[24:25], v[24:25], v[4:5]
	v_pk_fma_f32 v[2:3], v[26:27], v[26:27], v[2:3]
	s_waitcnt vmcnt(4)
	v_lshlrev_b32_e32 v20, 16, v220
	v_and_b32_e32 v21, 0xffff0000, v220
	v_lshlrev_b32_e32 v22, 16, v221
	v_and_b32_e32 v23, 0xffff0000, v221
	v_lshlrev_b32_e32 v24, 16, v222
	v_and_b32_e32 v25, 0xffff0000, v222
	v_lshlrev_b32_e32 v26, 16, v223
	v_and_b32_e32 v27, 0xffff0000, v223
	v_pk_fma_f32 v[8:9], v[20:21], v[20:21], v[8:9]
	v_pk_fma_f32 v[6:7], v[22:23], v[22:23], v[6:7]
	v_pk_fma_f32 v[4:5], v[24:25], v[24:25], v[4:5]
	v_pk_fma_f32 v[2:3], v[26:27], v[26:27], v[2:3]
	s_waitcnt vmcnt(3)
	v_lshlrev_b32_e32 v20, 16, v224
	v_and_b32_e32 v21, 0xffff0000, v224
	v_lshlrev_b32_e32 v22, 16, v225
	v_and_b32_e32 v23, 0xffff0000, v225
	v_lshlrev_b32_e32 v24, 16, v226
	v_and_b32_e32 v25, 0xffff0000, v226
	v_lshlrev_b32_e32 v26, 16, v227
	v_and_b32_e32 v27, 0xffff0000, v227
	v_pk_fma_f32 v[8:9], v[20:21], v[20:21], v[8:9]
	v_pk_fma_f32 v[6:7], v[22:23], v[22:23], v[6:7]
	v_pk_fma_f32 v[4:5], v[24:25], v[24:25], v[4:5]
	v_pk_fma_f32 v[2:3], v[26:27], v[26:27], v[2:3]
	s_waitcnt vmcnt(2)
	v_lshlrev_b32_e32 v20, 16, v228
	v_and_b32_e32 v21, 0xffff0000, v228
	v_lshlrev_b32_e32 v22, 16, v229
	v_and_b32_e32 v23, 0xffff0000, v229
	v_lshlrev_b32_e32 v24, 16, v230
	v_and_b32_e32 v25, 0xffff0000, v230
	v_lshlrev_b32_e32 v26, 16, v231
	v_and_b32_e32 v27, 0xffff0000, v231
	v_pk_fma_f32 v[8:9], v[20:21], v[20:21], v[8:9]
	v_pk_fma_f32 v[6:7], v[22:23], v[22:23], v[6:7]
	v_pk_fma_f32 v[4:5], v[24:25], v[24:25], v[4:5]
	v_pk_fma_f32 v[2:3], v[26:27], v[26:27], v[2:3]
	s_waitcnt vmcnt(1)
	v_lshlrev_b32_e32 v20, 16, v232
	v_and_b32_e32 v21, 0xffff0000, v232
	v_lshlrev_b32_e32 v22, 16, v233
	v_and_b32_e32 v23, 0xffff0000, v233
	v_lshlrev_b32_e32 v24, 16, v234
	v_and_b32_e32 v25, 0xffff0000, v234
	v_lshlrev_b32_e32 v26, 16, v235
	v_and_b32_e32 v27, 0xffff0000, v235
	v_pk_fma_f32 v[8:9], v[20:21], v[20:21], v[8:9]
	v_pk_fma_f32 v[6:7], v[22:23], v[22:23], v[6:7]
	v_pk_fma_f32 v[4:5], v[24:25], v[24:25], v[4:5]
	v_pk_fma_f32 v[2:3], v[26:27], v[26:27], v[2:3]
	s_waitcnt vmcnt(0)
	v_lshlrev_b32_e32 v20, 16, v236
	v_and_b32_e32 v21, 0xffff0000, v236
	v_lshlrev_b32_e32 v22, 16, v237
	v_and_b32_e32 v23, 0xffff0000, v237
	v_lshlrev_b32_e32 v24, 16, v238
	v_and_b32_e32 v25, 0xffff0000, v238
	v_lshlrev_b32_e32 v26, 16, v239
	v_and_b32_e32 v27, 0xffff0000, v239
	v_pk_fma_f32 v[8:9], v[20:21], v[20:21], v[8:9]
	v_pk_fma_f32 v[6:7], v[22:23], v[22:23], v[6:7]
	v_pk_fma_f32 v[4:5], v[24:25], v[24:25], v[4:5]
	v_pk_fma_f32 v[2:3], v[26:27], v[26:27], v[2:3]
	s_cmp_eq_u32 s46, 2
	s_cbranch_scc0 .LBB0_390
	v_and_b32_e32 v10, 64, v114
	v_xor_b32_e32 v1, 16, v114
	v_add_u32_e32 v12, 64, v10
	v_cmp_lt_i32_e32 vcc, v1, v12
	v_xor_b32_e32 v13, 32, v114
	s_nop 0
	v_cndmask_b32_e32 v1, v114, v1, vcc
	v_cmp_lt_i32_e32 vcc, v13, v12
	v_lshlrev_b32_e32 v1, 2, v1
	ds_bpermute_b32 v10, v1, v8
	v_cndmask_b32_e32 v14, v114, v13, vcc
	ds_bpermute_b32 v11, v1, v9
	ds_bpermute_b32 v12, v1, v6
	ds_bpermute_b32 v13, v1, v7
	v_lshlrev_b32_e32 v19, 2, v14
	ds_bpermute_b32 v14, v1, v4
	ds_bpermute_b32 v15, v1, v5
	ds_bpermute_b32 v16, v1, v2
	ds_bpermute_b32 v17, v1, v3
	s_waitcnt lgkmcnt(6)
	v_pk_add_f32 v[8:9], v[8:9], v[10:11]
	s_waitcnt lgkmcnt(4)
	v_pk_add_f32 v[6:7], v[6:7], v[12:13]
	s_waitcnt lgkmcnt(2)
	v_pk_add_f32 v[4:5], v[4:5], v[14:15]
	ds_bpermute_b32 v10, v19, v8
	s_waitcnt lgkmcnt(1)
	v_pk_add_f32 v[2:3], v[2:3], v[16:17]
	ds_bpermute_b32 v11, v19, v9
	ds_bpermute_b32 v12, v19, v6
	ds_bpermute_b32 v13, v19, v7
	ds_bpermute_b32 v14, v19, v4
	ds_bpermute_b32 v15, v19, v5
	ds_bpermute_b32 v16, v19, v2
	ds_bpermute_b32 v17, v19, v3
	v_bfe_u32 v19, v18, 4, 2
	v_and_b32_e32 v1, 15, v18
	v_cmp_eq_u32_e32 vcc, 0, v19
	s_and_saveexec_b64 s[8:9], vcc
	s_cbranch_execz .LBB0_393
	v_lshlrev_b32_e32 v20, 3, v18
	v_and_b32_e32 v20, 0xfffffe00, v20
	v_lshlrev_b32_e32 v21, 5, v1
	v_add3_u32 v20, 0, v20, v21
	s_waitcnt lgkmcnt(6)
	v_pk_add_f32 v[8:9], v[8:9], v[10:11]
	s_waitcnt lgkmcnt(4)
	v_pk_add_f32 v[10:11], v[6:7], v[12:13]
	s_waitcnt lgkmcnt(2)
	v_pk_add_f32 v[4:5], v[4:5], v[14:15]
	s_waitcnt lgkmcnt(0)
	v_pk_add_f32 v[6:7], v[2:3], v[16:17]
	ds_write_b128 v20, v[8:11]
	ds_write_b128 v20, v[4:7] offset:16

.LBB0_784:
	s_or_b64 exec, exec, s[4:5]
	v_mov_b32_e32 v9, v174
	s_waitcnt lgkmcnt(0)
	s_barrier
	s_cmpk_lt_i32 s2, 0xb00
	s_nop 0
	v_readfirstlane_b32 s5, v9
	s_cbranch_scc0 .LBB0_800
	v_lshlrev_b32_e32 v0, 4, v9
	v_add_u32_e32 v1, 0x2000, v0
	v_ashrrev_i32_e32 v2, 31, v1
	v_lshrrev_b32_e32 v2, 22, v2
	v_add_u32_e32 v2, v1, v2
	v_ashrrev_i32_e32 v8, 10, v2
	v_mul_i32_i24_e32 v2, 0x400, v8
	v_sub_u32_e32 v1, v1, v2
	v_lshrrev_b32_e32 v2, 4, v1
	v_bitop3_b32 v1, v2, v1, 32 bitop3:0x6c
	v_ashrrev_i32_e32 v2, 31, v1
	v_lshrrev_b32_e32 v2, 26, v2
	v_add_u32_e32 v2, v1, v2
	v_lshlrev_b32_e32 v3, 3, v8
	v_ashrrev_i32_e32 v10, 6, v2
	v_and_b32_e32 v3, -16, v3
	v_add_u32_e32 v3, v10, v3
	v_and_b32_e32 v4, 3, v10
	s_mov_b32 s1, 0xfffe0
	v_lshrrev_b32_e32 v5, 2, v3
	v_lshlrev_b32_e32 v6, 1, v3
	v_and_b32_e32 v2, 0xc0, v2
	v_and_or_b32 v4, v3, s1, v4
	v_and_b32_e32 v5, 4, v5
	v_and_b32_e32 v6, 24, v6
	v_sub_u32_e32 v1, v1, v2
	v_mov_b32_e32 v2, 1
	v_or3_b32 v4, v4, v5, v6
	v_lshlrev_b32_e32 v5, 5, v8
	v_ashrrev_i16_sdwa v1, v2, sext(v1) dst_sel:DWORD dst_unused:UNUSED_PAD src0_sel:DWORD src1_sel:BYTE_0
	v_and_b32_e32 v5, 32, v5
	v_bfe_i32 v11, v1, 0, 16
	v_add_lshl_u32 v1, v5, v11, 1
	v_lshl_add_u32 v128, v4, 12, v1
	v_lshl_add_u32 v130, v3, 12, v1
	v_bfe_i32 v1, v9, 27, 1
	v_lshrrev_b32_e32 v1, 22, v1
	v_add_u32_e32 v1, v0, v1
	v_and_b32_e32 v1, 0xfffffc00, v1
	v_sub_u32_e32 v0, v0, v1
	v_lshrrev_b32_e32 v1, 4, v0
	v_ashrrev_i32_e32 v3, 31, v9
	v_bitop3_b32 v0, v1, v0, 32 bitop3:0x6c
	v_lshrrev_b32_e32 v3, 26, v3
	v_ashrrev_i32_e32 v1, 31, v0
	v_add_u32_e32 v3, v9, v3
	v_lshrrev_b32_e32 v1, 26, v1
	v_ashrrev_i32_e32 v13, 6, v3
	v_add_u32_e32 v1, v0, v1
	v_lshlrev_b32_e32 v3, 3, v13
	s_ashr_i32 s18, s5, 6
	v_ashrrev_i32_e32 v12, 6, v1
	v_and_b32_e32 v3, -16, v3
	v_readlane_b32 s6, v240, 20
	s_ashr_i32 s24, s5, 8
	s_lshl_b32 s0, s18, 10
	v_add_u32_e32 v3, v12, v3
	v_and_b32_e32 v4, 3, v12
	v_readlane_b32 s7, v240, 21
	v_and_or_b32 v4, v3, s1, v4
	s_movk_i32 s1, 0x161
	s_and_b64 s[6:7], s[6:7], exec
	s_cselect_b32 s4, s1, 0x160
	v_readlane_b32 s6, v240, 29
	s_mul_i32 s4, s6, s4
	v_readlane_b32 s6, v240, 24
	s_add_i32 s4, s4, s6
	s_mul_hi_i32 s6, s4, 0x2e8ba2e9
	s_lshr_b32 s7, s6, 31
	s_ashr_i32 s6, s6, 5
	s_add_i32 s6, s6, s7
	s_lshl_b32 s7, s6, 2
	s_mulk_i32 s6, 0xb0
	s_sub_i32 s6, s4, s6
	s_lshr_b32 s4, s6, 1
	s_and_b32 s4, s4, 0xfffe
	s_and_b32 s6, s6, 3
	v_lshrrev_b32_e32 v5, 2, v3
	v_lshlrev_b32_e32 v6, 1, v3
	v_and_b32_e32 v1, 0xc0, v1
	s_lshr_b32 s4, s4, 1
	s_add_i32 s40, s7, s6
	v_and_b32_e32 v5, 4, v5
	v_and_b32_e32 v6, 24, v6
	v_sub_u32_e32 v0, v0, v1
	s_ashr_i32 s41, s40, 31
	s_bfe_i64 s[10:11], s[4:5], 0x100000
	v_or3_b32 v4, v4, v5, v6
	v_lshlrev_b32_e32 v5, 5, v13
	v_ashrrev_i16_sdwa v0, v2, sext(v0) dst_sel:DWORD dst_unused:UNUSED_PAD src0_sel:DWORD src1_sel:BYTE_0
	s_lshl_b64 s[6:7], s[40:41], 20
	s_lshl_b64 s[10:11], s[10:11], 20
	v_and_b32_e32 v5, 32, v5
	v_bfe_i32 v14, v0, 0, 16
	s_add_u32 s44, s20, s10
	v_add_lshl_u32 v0, v5, v14, 1
	s_addc_u32 s45, s21, s11
	s_add_i32 s10, s0, 0
	v_lshl_add_u32 v132, v4, 12, v0
	s_add_i32 m0, s10, 0x10000
	v_lshl_add_u32 v134, v3, 12, v0
	global_load_lds_dwordx4 v132, s[44:45]
	s_add_i32 m0, s10, 0x12000
	s_add_u32 s14, s44, 0x80000
	global_load_lds_dwordx4 v128, s[44:45]
	s_addc_u32 s15, s45, 0
	s_add_i32 m0, s10, 0x14000
	v_mov_b32_e32 v133, 0
	global_load_lds_dwordx4 v132, s[14:15]
	s_add_i32 m0, s10, 0x16000
	s_add_u32 s42, s28, s6
	s_addc_u32 s43, s29, s7
	s_add_i32 s11, s10, 0x2000
	global_load_lds_dwordx4 v128, s[14:15]
	s_mov_b32 m0, s10
	s_add_u32 s6, s42, 0x80000
	global_load_lds_dwordx4 v134, s[42:43]
	s_mov_b32 m0, s11
	s_addc_u32 s7, s43, 0
	s_add_i32 s14, s10, 0x4000
	global_load_lds_dwordx4 v130, s[42:43]
	s_mov_b32 m0, s14
	s_add_i32 s15, s10, 0x6000
	global_load_lds_dwordx4 v134, s[6:7]
	s_mov_b32 m0, s15
	v_mov_b32_e32 v129, v133
	global_load_lds_dwordx4 v130, s[6:7]
	v_mov_b32_e32 v135, v133
	v_mov_b32_e32 v131, v133
	s_cmp_eq_u32 s24, 1
	s_mov_b32 s33, 0
	v_lshl_add_u64 v[6:7], s[44:45], 0, v[132:133]
	v_lshl_add_u64 v[4:5], s[44:45], 0, v[128:129]
	v_lshl_add_u64 v[0:1], s[42:43], 0, v[134:135]
	s_cselect_b64 s[6:7], -1, 0
	s_cmp_lg_u32 s24, 1
	v_lshl_add_u64 v[2:3], s[42:43], 0, v[130:131]
	s_cbranch_scc1 .LBB0_787

.LBB0_790:
	s_add_i32 s33, s33, 1
	s_mul_i32 s4, s33, s31
	s_mul_hi_u32 s5, s33, s58
	s_add_i32 s5, s5, s4
	s_mul_i32 s4, s33, s58
	s_add_u32 s36, s4, s2
	s_addc_u32 s37, s5, s3
	v_cmp_gt_i64_e32 vcc, s[36:37], v[142:143]
	v_cmp_lt_i64_e64 s[4:5], s[36:37], v[140:141]
	s_cbranch_vccnz .LBB0_792
	s_ashr_i32 s26, s36, 31
	s_lshr_b32 s26, s26, 29
	s_add_i32 s26, s36, s26
	s_ashr_i32 s27, s26, 3
	s_and_b32 s26, s26, -8
	s_sub_i32 s26, s36, s26
	s_cmp_lt_i32 s26, 0
	s_cselect_b32 s34, s1, 0x160
	s_mul_i32 s26, s26, s34
	s_add_i32 s26, s26, s27
	s_mul_hi_i32 s27, s26, 0x2e8ba2e9
	s_lshr_b32 s34, s27, 31
	s_ashr_i32 s27, s27, 5
	s_add_i32 s27, s27, s34
	s_lshl_b32 s34, s27, 2
	s_sub_i32 s35, 64, s34
	s_min_i32 s35, s35, 4
	s_abs_i32 s36, s35
	v_cvt_f32_u32_e32 v0, s36
	s_sub_i32 s38, 0, s36
	s_mulk_i32 s27, 0xb0
	s_sub_i32 s27, s26, s27
	v_rcp_iflag_f32_e32 v0, v0
	s_abs_i32 s26, s27
	s_xor_b32 s37, s27, s35
	s_ashr_i32 s37, s37, 31
	v_mul_f32_e32 v0, 0x4f7ffffe, v0
	v_cvt_u32_f32_e32 v0, v0
	s_nop 0
	v_readfirstlane_b32 s39, v0
	s_mul_i32 s38, s38, s39
	s_mul_hi_u32 s38, s39, s38
	s_add_i32 s39, s39, s38
	s_mul_hi_u32 s38, s26, s39
	s_mul_i32 s39, s38, s36
	s_sub_i32 s26, s26, s39
	s_add_i32 s46, s38, 1
	s_sub_i32 s39, s26, s36
	s_cmp_ge_u32 s26, s36
	s_cselect_b32 s38, s46, s38
	s_cselect_b32 s26, s39, s26
	s_add_i32 s39, s38, 1
	s_cmp_ge_u32 s26, s36
	s_cselect_b32 s26, s39, s38
	s_xor_b32 s26, s26, s37
	s_sub_i32 s26, s26, s37
	s_mul_i32 s35, s26, s35
	s_sub_i32 s27, s27, s35
	s_add_i32 s34, s34, s27
.LBB0_792:
	s_ashr_i32 s35, s34, 31
	s_lshl_b64 s[36:37], s[34:35], 20
	s_add_u32 s36, s28, s36
	s_addc_u32 s37, s29, s37
	s_and_b64 s[38:39], s[4:5], exec
	s_cselect_b32 s35, s37, s43
	s_cselect_b32 s61, s36, s42
	s_ashr_i32 s27, s26, 31
	s_lshl_b64 s[38:39], s[26:27], 20
	s_add_u32 s38, s20, s38
	s_addc_u32 s39, s21, s39
	s_and_b64 s[46:47], s[4:5], exec
	s_cselect_b32 s27, s39, s45
	s_cselect_b32 s62, s38, s44
	s_add_u32 s42, s42, 0x80080
	s_addc_u32 s43, s43, 0
	s_add_u32 s63, s44, 0x100
	v_mov_b32_e32 v0, 0
	s_addc_u32 s64, s45, 0
	s_mov_b32 s65, -2
	v_mov_b32_e32 v1, v0
	v_mov_b32_e32 v2, v0
	v_mov_b32_e32 v3, v0
	v_mov_b32_e32 v4, v0
	v_mov_b32_e32 v5, v0
	v_mov_b32_e32 v6, v0
	v_mov_b32_e32 v7, v0
	v_mov_b32_e32 v16, v0
	v_mov_b32_e32 v17, v0
	v_mov_b32_e32 v18, v0
	v_mov_b32_e32 v19, v0
	v_mov_b32_e32 v20, v0
	v_mov_b32_e32 v21, v0
	v_mov_b32_e32 v22, v0
	v_mov_b32_e32 v23, v0
	v_mov_b32_e32 v32, v0
	v_mov_b32_e32 v33, v0
	v_mov_b32_e32 v34, v0
	v_mov_b32_e32 v35, v0
	v_mov_b32_e32 v36, v0
	v_mov_b32_e32 v37, v0
	v_mov_b32_e32 v38, v0
	v_mov_b32_e32 v39, v0
	v_mov_b32_e32 v48, v0
	v_mov_b32_e32 v49, v0
	v_mov_b32_e32 v50, v0
	v_mov_b32_e32 v51, v0
	v_mov_b32_e32 v52, v0
	v_mov_b32_e32 v53, v0
	v_mov_b32_e32 v54, v0
	v_mov_b32_e32 v55, v0
	v_mov_b32_e32 v8, v0
	v_mov_b32_e32 v9, v0
	v_mov_b32_e32 v10, v0
	v_mov_b32_e32 v11, v0
	v_mov_b32_e32 v12, v0
	v_mov_b32_e32 v13, v0
	v_mov_b32_e32 v14, v0
	v_mov_b32_e32 v15, v0
	v_mov_b32_e32 v24, v0
	v_mov_b32_e32 v25, v0
	v_mov_b32_e32 v26, v0
	v_mov_b32_e32 v27, v0
	v_mov_b32_e32 v28, v0
	v_mov_b32_e32 v29, v0
	v_mov_b32_e32 v30, v0
	v_mov_b32_e32 v31, v0
	v_mov_b32_e32 v40, v0
	v_mov_b32_e32 v41, v0
	v_mov_b32_e32 v42, v0
	v_mov_b32_e32 v43, v0
	v_mov_b32_e32 v44, v0
	v_mov_b32_e32 v45, v0
	v_mov_b32_e32 v46, v0
	v_mov_b32_e32 v47, v0
	v_mov_b32_e32 v56, v0
	v_mov_b32_e32 v57, v0
	v_mov_b32_e32 v58, v0
	v_mov_b32_e32 v59, v0
	v_mov_b32_e32 v60, v0
	v_mov_b32_e32 v61, v0
	v_mov_b32_e32 v62, v0
	v_mov_b32_e32 v63, v0
	v_mov_b32_e32 v64, v0
	v_mov_b32_e32 v65, v0
	v_mov_b32_e32 v66, v0
	v_mov_b32_e32 v67, v0
	v_mov_b32_e32 v68, v0
	v_mov_b32_e32 v69, v0
	v_mov_b32_e32 v70, v0
	v_mov_b32_e32 v71, v0
	v_mov_b32_e32 v80, v0
	v_mov_b32_e32 v81, v0
	v_mov_b32_e32 v82, v0
	v_mov_b32_e32 v83, v0
	v_mov_b32_e32 v84, v0
	v_mov_b32_e32 v85, v0
	v_mov_b32_e32 v86, v0
	v_mov_b32_e32 v87, v0
	v_mov_b32_e32 v96, v0
	v_mov_b32_e32 v97, v0
	v_mov_b32_e32 v98, v0
	v_mov_b32_e32 v99, v0
	v_mov_b32_e32 v100, v0
	v_mov_b32_e32 v101, v0
	v_mov_b32_e32 v102, v0
	v_mov_b32_e32 v103, v0
	v_mov_b32_e32 v112, v0
	v_mov_b32_e32 v113, v0
	v_mov_b32_e32 v114, v0
	v_mov_b32_e32 v115, v0
	v_mov_b32_e32 v116, v0
	v_mov_b32_e32 v117, v0
	v_mov_b32_e32 v118, v0
	v_mov_b32_e32 v119, v0
	v_mov_b32_e32 v72, v0
	v_mov_b32_e32 v73, v0
	v_mov_b32_e32 v74, v0
	v_mov_b32_e32 v75, v0
	v_mov_b32_e32 v76, v0
	v_mov_b32_e32 v77, v0
	v_mov_b32_e32 v78, v0
	v_mov_b32_e32 v79, v0
	v_mov_b32_e32 v88, v0
	v_mov_b32_e32 v89, v0
	v_mov_b32_e32 v90, v0
	v_mov_b32_e32 v91, v0
	v_mov_b32_e32 v92, v0
	v_mov_b32_e32 v93, v0
	v_mov_b32_e32 v94, v0
	v_mov_b32_e32 v95, v0
	v_mov_b32_e32 v104, v0
	v_mov_b32_e32 v105, v0
	v_mov_b32_e32 v106, v0
	v_mov_b32_e32 v107, v0
	v_mov_b32_e32 v108, v0
	v_mov_b32_e32 v109, v0
	v_mov_b32_e32 v110, v0
	v_mov_b32_e32 v111, v0
	v_mov_b32_e32 v120, v0
	v_mov_b32_e32 v121, v0
	v_mov_b32_e32 v122, v0
	v_mov_b32_e32 v123, v0
	v_mov_b32_e32 v124, v0
	v_mov_b32_e32 v125, v0
	v_mov_b32_e32 v126, v0
	v_mov_b32_e32 v127, v0
	s_and_b64 vcc, exec, s[24:25]
	s_cbranch_vccz .Lp7_kloop_h1
.LBB0_793:
	ds_read_b128 v[144:147], v153
	ds_read_b128 v[158:161], v153 offset:1024
	ds_read_b128 v[162:165], v153 offset:2048
	ds_read_b128 v[166:169], v153 offset:3072
	ds_read_b128 v[170:173], v154
	ds_read_b128 v[176:179], v154 offset:1024
	ds_read_b128 v[180:183], v154 offset:2048
	ds_read_b128 v[184:187], v154 offset:3072
	s_add_u32 s44, s42, 0xfff80080
	s_addc_u32 s45, s43, -1
	s_cmp_eq_u32 s65, 28
	s_cselect_b32 s47, s35, s45
	s_cselect_b32 s46, s61, s44
	s_cselect_b32 s45, s27, s64
	s_cselect_b32 s44, s62, s63
	s_add_u32 s100, s46, 0x80
	s_addc_u32 s101, s47, 0
	s_add_i32 m0, s10, 0xc000
	ds_read_b128 v[188:191], v155
	ds_read_b128 v[192:195], v155 offset:1024
	ds_read_b128 v[196:199], v155 offset:2048
	ds_read_b128 v[200:203], v155 offset:3072
	ds_read_b128 v[204:207], v155 offset:4096
	ds_read_b128 v[208:211], v155 offset:5120
	ds_read_b128 v[212:215], v155 offset:6144
	ds_read_b128 v[216:219], v155 offset:7168
	global_load_lds_dwordx4 v136, s[42:43]
	s_add_i32 m0, s10, 0xe000
	s_nop 0
	global_load_lds_dwordx4 v138, s[42:43]
	s_waitcnt vmcnt(8)
	s_waitcnt lgkmcnt(0)
	s_setprio 1
	s_waitcnt lgkmcnt(0)
	v_mfma_f32_16x16x32_bf16 v[124:127], v[144:147], v[188:191], v[124:127]
	v_mfma_f32_16x16x32_bf16 v[120:123], v[162:165], v[188:191], v[120:123]
	v_mfma_f32_16x16x32_bf16 v[108:111], v[144:147], v[196:199], v[108:111]
	v_mfma_f32_16x16x32_bf16 v[104:107], v[162:165], v[196:199], v[104:107]
	v_mfma_f32_16x16x32_bf16 v[92:95], v[144:147], v[204:207], v[92:95]
	v_mfma_f32_16x16x32_bf16 v[88:91], v[162:165], v[204:207], v[88:91]
	v_mfma_f32_16x16x32_bf16 v[76:79], v[144:147], v[212:215], v[76:79]
	v_mfma_f32_16x16x32_bf16 v[72:75], v[162:165], v[212:215], v[72:75]
	v_mfma_f32_16x16x32_bf16 v[124:127], v[158:161], v[192:195], v[124:127]
	v_mfma_f32_16x16x32_bf16 v[120:123], v[166:169], v[192:195], v[120:123]
	v_mfma_f32_16x16x32_bf16 v[108:111], v[158:161], v[200:203], v[108:111]
	v_mfma_f32_16x16x32_bf16 v[104:107], v[166:169], v[200:203], v[104:107]
	v_mfma_f32_16x16x32_bf16 v[92:95], v[158:161], v[208:211], v[92:95]
	v_mfma_f32_16x16x32_bf16 v[88:91], v[166:169], v[208:211], v[88:91]
	v_mfma_f32_16x16x32_bf16 v[76:79], v[158:161], v[216:219], v[76:79]
	v_mfma_f32_16x16x32_bf16 v[72:75], v[166:169], v[216:219], v[72:75]
	s_setprio 0
	s_setprio 1
	v_mfma_f32_16x16x32_bf16 v[116:119], v[170:173], v[188:191], v[116:119]
	v_mfma_f32_16x16x32_bf16 v[112:115], v[180:183], v[188:191], v[112:115]
	v_mfma_f32_16x16x32_bf16 v[100:103], v[170:173], v[196:199], v[100:103]
	v_mfma_f32_16x16x32_bf16 v[96:99], v[180:183], v[196:199], v[96:99]
	v_mfma_f32_16x16x32_bf16 v[84:87], v[170:173], v[204:207], v[84:87]
	v_mfma_f32_16x16x32_bf16 v[80:83], v[180:183], v[204:207], v[80:83]
	v_mfma_f32_16x16x32_bf16 v[68:71], v[170:173], v[212:215], v[68:71]
	v_mfma_f32_16x16x32_bf16 v[64:67], v[180:183], v[212:215], v[64:67]
	v_mfma_f32_16x16x32_bf16 v[116:119], v[176:179], v[192:195], v[116:119]
	v_mfma_f32_16x16x32_bf16 v[112:115], v[184:187], v[192:195], v[112:115]
	v_mfma_f32_16x16x32_bf16 v[100:103], v[176:179], v[200:203], v[100:103]
	v_mfma_f32_16x16x32_bf16 v[96:99], v[184:187], v[200:203], v[96:99]
	v_mfma_f32_16x16x32_bf16 v[84:87], v[176:179], v[208:211], v[84:87]
	v_mfma_f32_16x16x32_bf16 v[80:83], v[184:187], v[208:211], v[80:83]
	v_mfma_f32_16x16x32_bf16 v[68:71], v[176:179], v[216:219], v[68:71]
	v_mfma_f32_16x16x32_bf16 v[64:67], v[184:187], v[216:219], v[64:67]
	s_setprio 0
	s_barrier
	s_add_i32 s66, s49, s0
	s_mov_b32 m0, s66
	ds_read_b128 v[188:191], v155 offset:16384
	ds_read_b128 v[192:195], v155 offset:17408
	ds_read_b128 v[196:199], v155 offset:18432
	ds_read_b128 v[200:203], v155 offset:19456
	ds_read_b128 v[204:207], v155 offset:20480
	ds_read_b128 v[208:211], v155 offset:21504
	ds_read_b128 v[212:215], v155 offset:22528
	ds_read_b128 v[216:219], v155 offset:23552
	global_load_lds_dwordx4 v132, s[44:45]
	s_add_i32 m0, s66, 0x2000
	s_add_u32 s66, s44, 0x80000
	s_addc_u32 s67, s45, 0
	s_add_i32 s68, s50, s0
	global_load_lds_dwordx4 v128, s[44:45]
	s_mov_b32 m0, s68
	s_nop 0
	global_load_lds_dwordx4 v132, s[66:67]
	s_add_i32 m0, s68, 0x2000
	s_nop 0
	global_load_lds_dwordx4 v128, s[66:67]
	s_mov_b32 m0, s10
	s_nop 0
	global_load_lds_dwordx4 v134, s[46:47]
	s_mov_b32 m0, s11
	s_nop 0
	global_load_lds_dwordx4 v130, s[46:47]
	s_waitcnt vmcnt(8)
	s_waitcnt lgkmcnt(0)
	s_setprio 1
	s_waitcnt lgkmcnt(0)
	v_mfma_f32_16x16x32_bf16 v[60:63], v[144:147], v[188:191], v[60:63]
	v_mfma_f32_16x16x32_bf16 v[56:59], v[162:165], v[188:191], v[56:59]
	v_mfma_f32_16x16x32_bf16 v[44:47], v[144:147], v[196:199], v[44:47]
	v_mfma_f32_16x16x32_bf16 v[40:43], v[162:165], v[196:199], v[40:43]
	v_mfma_f32_16x16x32_bf16 v[28:31], v[144:147], v[204:207], v[28:31]
	v_mfma_f32_16x16x32_bf16 v[24:27], v[162:165], v[204:207], v[24:27]
	v_mfma_f32_16x16x32_bf16 v[12:15], v[144:147], v[212:215], v[12:15]
	v_mfma_f32_16x16x32_bf16 v[8:11], v[162:165], v[212:215], v[8:11]
	v_mfma_f32_16x16x32_bf16 v[60:63], v[158:161], v[192:195], v[60:63]
	v_mfma_f32_16x16x32_bf16 v[56:59], v[166:169], v[192:195], v[56:59]
	v_mfma_f32_16x16x32_bf16 v[44:47], v[158:161], v[200:203], v[44:47]
	v_mfma_f32_16x16x32_bf16 v[40:43], v[166:169], v[200:203], v[40:43]
	v_mfma_f32_16x16x32_bf16 v[28:31], v[158:161], v[208:211], v[28:31]
	v_mfma_f32_16x16x32_bf16 v[24:27], v[166:169], v[208:211], v[24:27]
	v_mfma_f32_16x16x32_bf16 v[12:15], v[158:161], v[216:219], v[12:15]
	v_mfma_f32_16x16x32_bf16 v[8:11], v[166:169], v[216:219], v[8:11]
	s_setprio 0
	s_setprio 1
	v_mfma_f32_16x16x32_bf16 v[52:55], v[170:173], v[188:191], v[52:55]
	v_mfma_f32_16x16x32_bf16 v[48:51], v[180:183], v[188:191], v[48:51]
	v_mfma_f32_16x16x32_bf16 v[36:39], v[170:173], v[196:199], v[36:39]
	v_mfma_f32_16x16x32_bf16 v[32:35], v[180:183], v[196:199], v[32:35]
	v_mfma_f32_16x16x32_bf16 v[20:23], v[170:173], v[204:207], v[20:23]
	v_mfma_f32_16x16x32_bf16 v[16:19], v[180:183], v[204:207], v[16:19]
	v_mfma_f32_16x16x32_bf16 v[4:7], v[170:173], v[212:215], v[4:7]
	v_mfma_f32_16x16x32_bf16 v[0:3], v[180:183], v[212:215], v[0:3]
	v_mfma_f32_16x16x32_bf16 v[52:55], v[176:179], v[192:195], v[52:55]
	v_mfma_f32_16x16x32_bf16 v[48:51], v[184:187], v[192:195], v[48:51]
	v_mfma_f32_16x16x32_bf16 v[36:39], v[176:179], v[200:203], v[36:39]
	v_mfma_f32_16x16x32_bf16 v[32:35], v[184:187], v[200:203], v[32:35]
	v_mfma_f32_16x16x32_bf16 v[20:23], v[176:179], v[208:211], v[20:23]
	v_mfma_f32_16x16x32_bf16 v[16:19], v[184:187], v[208:211], v[16:19]
	v_mfma_f32_16x16x32_bf16 v[4:7], v[176:179], v[216:219], v[4:7]
	v_mfma_f32_16x16x32_bf16 v[0:3], v[184:187], v[216:219], v[0:3]
	s_setprio 0
	s_barrier
	s_add_i32 s66, 0, 0x18000
	v_add_u32_e32 v157, s66, v151
	s_add_i32 s67, 0, 0x1c000
	ds_read_b128 v[144:147], v157
	ds_read_b128 v[158:161], v157 offset:1024
	ds_read_b128 v[162:165], v157 offset:2048
	ds_read_b128 v[166:169], v157 offset:3072
	v_add_u32_e32 v157, s67, v151
	ds_read_b128 v[170:173], v157
	ds_read_b128 v[176:179], v157 offset:1024
	ds_read_b128 v[180:183], v157 offset:2048
	ds_read_b128 v[184:187], v157 offset:3072
	s_add_u32 s46, s46, 0x80000
	s_addc_u32 s47, s47, 0
	s_mov_b32 m0, s14
	ds_read_b128 v[188:191], v155 offset:32768
	ds_read_b128 v[192:195], v155 offset:33792
	ds_read_b128 v[196:199], v155 offset:34816
	ds_read_b128 v[200:203], v155 offset:35840
	ds_read_b128 v[204:207], v155 offset:36864
	ds_read_b128 v[208:211], v155 offset:37888
	ds_read_b128 v[212:215], v155 offset:38912
	ds_read_b128 v[216:219], v155 offset:39936
	global_load_lds_dwordx4 v134, s[46:47]
	s_mov_b32 m0, s15
	s_nop 0
	global_load_lds_dwordx4 v130, s[46:47]
	s_waitcnt vmcnt(8)
	s_waitcnt lgkmcnt(0)
	s_setprio 1
	s_waitcnt lgkmcnt(0)
	v_mfma_f32_16x16x32_bf16 v[124:127], v[144:147], v[188:191], v[124:127]
	v_mfma_f32_16x16x32_bf16 v[120:123], v[162:165], v[188:191], v[120:123]
	v_mfma_f32_16x16x32_bf16 v[108:111], v[144:147], v[196:199], v[108:111]
	v_mfma_f32_16x16x32_bf16 v[104:107], v[162:165], v[196:199], v[104:107]
	v_mfma_f32_16x16x32_bf16 v[92:95], v[144:147], v[204:207], v[92:95]
	v_mfma_f32_16x16x32_bf16 v[88:91], v[162:165], v[204:207], v[88:91]
	v_mfma_f32_16x16x32_bf16 v[76:79], v[144:147], v[212:215], v[76:79]
	v_mfma_f32_16x16x32_bf16 v[72:75], v[162:165], v[212:215], v[72:75]
	v_mfma_f32_16x16x32_bf16 v[124:127], v[158:161], v[192:195], v[124:127]
	v_mfma_f32_16x16x32_bf16 v[120:123], v[166:169], v[192:195], v[120:123]
	v_mfma_f32_16x16x32_bf16 v[108:111], v[158:161], v[200:203], v[108:111]
	v_mfma_f32_16x16x32_bf16 v[104:107], v[166:169], v[200:203], v[104:107]
	v_mfma_f32_16x16x32_bf16 v[92:95], v[158:161], v[208:211], v[92:95]
	v_mfma_f32_16x16x32_bf16 v[88:91], v[166:169], v[208:211], v[88:91]
	v_mfma_f32_16x16x32_bf16 v[76:79], v[158:161], v[216:219], v[76:79]
	v_mfma_f32_16x16x32_bf16 v[72:75], v[166:169], v[216:219], v[72:75]
	s_setprio 0
	s_setprio 1
	v_mfma_f32_16x16x32_bf16 v[116:119], v[170:173], v[188:191], v[116:119]
	v_mfma_f32_16x16x32_bf16 v[112:115], v[180:183], v[188:191], v[112:115]
	v_mfma_f32_16x16x32_bf16 v[100:103], v[170:173], v[196:199], v[100:103]
	v_mfma_f32_16x16x32_bf16 v[96:99], v[180:183], v[196:199], v[96:99]
	v_mfma_f32_16x16x32_bf16 v[84:87], v[170:173], v[204:207], v[84:87]
	v_mfma_f32_16x16x32_bf16 v[80:83], v[180:183], v[204:207], v[80:83]
	v_mfma_f32_16x16x32_bf16 v[68:71], v[170:173], v[212:215], v[68:71]
	v_mfma_f32_16x16x32_bf16 v[64:67], v[180:183], v[212:215], v[64:67]
	v_mfma_f32_16x16x32_bf16 v[116:119], v[176:179], v[192:195], v[116:119]
	v_mfma_f32_16x16x32_bf16 v[112:115], v[184:187], v[192:195], v[112:115]
	v_mfma_f32_16x16x32_bf16 v[100:103], v[176:179], v[200:203], v[100:103]
	v_mfma_f32_16x16x32_bf16 v[96:99], v[184:187], v[200:203], v[96:99]
	v_mfma_f32_16x16x32_bf16 v[84:87], v[176:179], v[208:211], v[84:87]
	v_mfma_f32_16x16x32_bf16 v[80:83], v[184:187], v[208:211], v[80:83]
	v_mfma_f32_16x16x32_bf16 v[68:71], v[176:179], v[216:219], v[68:71]
	v_mfma_f32_16x16x32_bf16 v[64:67], v[184:187], v[216:219], v[64:67]
	s_setprio 0
	s_barrier
	s_add_i32 s46, s66, s0
	s_add_u32 s98, s44, 0x80
	s_addc_u32 s99, s45, 0
	s_mov_b32 m0, s46
	ds_read_b128 v[188:191], v155 offset:49152
	ds_read_b128 v[192:195], v155 offset:50176
	ds_read_b128 v[196:199], v155 offset:51200
	ds_read_b128 v[200:203], v155 offset:52224
	ds_read_b128 v[204:207], v155 offset:53248
	ds_read_b128 v[208:211], v155 offset:54272
	ds_read_b128 v[212:215], v155 offset:55296
	ds_read_b128 v[216:219], v155 offset:56320
	global_load_lds_dwordx4 v132, s[98:99]
	s_add_i32 m0, s46, 0x2000
	s_add_u32 s44, s44, 0x80080
	s_addc_u32 s45, s45, 0
	s_add_i32 s46, s67, s0
	global_load_lds_dwordx4 v128, s[98:99]
	s_mov_b32 m0, s46
	s_nop 0
	global_load_lds_dwordx4 v132, s[44:45]
	s_add_i32 m0, s46, 0x2000
	s_nop 0
	global_load_lds_dwordx4 v128, s[44:45]
	s_mov_b32 m0, s41
	s_nop 0
	global_load_lds_dwordx4 v134, s[100:101]
	s_mov_b32 m0, s48
	s_nop 0
	global_load_lds_dwordx4 v130, s[100:101]
	s_waitcnt vmcnt(8)
	s_waitcnt lgkmcnt(0)
	s_setprio 1
	s_waitcnt lgkmcnt(0)
	v_mfma_f32_16x16x32_bf16 v[60:63], v[144:147], v[188:191], v[60:63]
	v_mfma_f32_16x16x32_bf16 v[56:59], v[162:165], v[188:191], v[56:59]
	v_mfma_f32_16x16x32_bf16 v[44:47], v[144:147], v[196:199], v[44:47]
	v_mfma_f32_16x16x32_bf16 v[40:43], v[162:165], v[196:199], v[40:43]
	v_mfma_f32_16x16x32_bf16 v[28:31], v[144:147], v[204:207], v[28:31]
	v_mfma_f32_16x16x32_bf16 v[24:27], v[162:165], v[204:207], v[24:27]
	v_mfma_f32_16x16x32_bf16 v[12:15], v[144:147], v[212:215], v[12:15]
	v_mfma_f32_16x16x32_bf16 v[8:11], v[162:165], v[212:215], v[8:11]
	v_mfma_f32_16x16x32_bf16 v[60:63], v[158:161], v[192:195], v[60:63]
	v_mfma_f32_16x16x32_bf16 v[56:59], v[166:169], v[192:195], v[56:59]
	v_mfma_f32_16x16x32_bf16 v[44:47], v[158:161], v[200:203], v[44:47]
	v_mfma_f32_16x16x32_bf16 v[40:43], v[166:169], v[200:203], v[40:43]
	v_mfma_f32_16x16x32_bf16 v[28:31], v[158:161], v[208:211], v[28:31]
	v_mfma_f32_16x16x32_bf16 v[24:27], v[166:169], v[208:211], v[24:27]
	v_mfma_f32_16x16x32_bf16 v[12:15], v[158:161], v[216:219], v[12:15]
	v_mfma_f32_16x16x32_bf16 v[8:11], v[166:169], v[216:219], v[8:11]
	s_setprio 0
	s_setprio 1
	v_mfma_f32_16x16x32_bf16 v[52:55], v[170:173], v[188:191], v[52:55]
	v_mfma_f32_16x16x32_bf16 v[48:51], v[180:183], v[188:191], v[48:51]
	v_mfma_f32_16x16x32_bf16 v[36:39], v[170:173], v[196:199], v[36:39]
	v_mfma_f32_16x16x32_bf16 v[32:35], v[180:183], v[196:199], v[32:35]
	v_mfma_f32_16x16x32_bf16 v[20:23], v[170:173], v[204:207], v[20:23]
	v_mfma_f32_16x16x32_bf16 v[16:19], v[180:183], v[204:207], v[16:19]
	v_mfma_f32_16x16x32_bf16 v[4:7], v[170:173], v[212:215], v[4:7]
	v_mfma_f32_16x16x32_bf16 v[0:3], v[180:183], v[212:215], v[0:3]
	v_mfma_f32_16x16x32_bf16 v[52:55], v[176:179], v[192:195], v[52:55]
	v_mfma_f32_16x16x32_bf16 v[48:51], v[184:187], v[192:195], v[48:51]
	v_mfma_f32_16x16x32_bf16 v[36:39], v[176:179], v[200:203], v[36:39]
	v_mfma_f32_16x16x32_bf16 v[32:35], v[184:187], v[200:203], v[32:35]
	v_mfma_f32_16x16x32_bf16 v[20:23], v[176:179], v[208:211], v[20:23]
	v_mfma_f32_16x16x32_bf16 v[16:19], v[184:187], v[208:211], v[16:19]
	v_mfma_f32_16x16x32_bf16 v[4:7], v[176:179], v[216:219], v[4:7]
	v_mfma_f32_16x16x32_bf16 v[0:3], v[184:187], v[216:219], v[0:3]
	s_setprio 0
	s_barrier
	s_add_i32 s65, s65, 2
	s_add_u32 s42, s42, 0x100
	s_addc_u32 s43, s43, 0
	s_add_u32 s63, s63, 0x100
	s_addc_u32 s64, s64, 0
	s_cmp_gt_u32 s65, 29
	s_cbranch_scc0 .LBB0_793
	s_branch .Lp7_kloop_done
.Lp7_kloop_h1:
	ds_read_b128 v[144:147], v153
	ds_read_b128 v[158:161], v153 offset:1024
	ds_read_b128 v[162:165], v153 offset:2048
	ds_read_b128 v[166:169], v153 offset:3072
	ds_read_b128 v[170:173], v154
	ds_read_b128 v[176:179], v154 offset:1024
	ds_read_b128 v[180:183], v154 offset:2048
	ds_read_b128 v[184:187], v154 offset:3072
	s_add_u32 s44, s42, 0xfff80080
	s_addc_u32 s45, s43, -1
	s_cmp_eq_u32 s65, 28
	s_cselect_b32 s47, s35, s45
	s_cselect_b32 s46, s61, s44
	s_cselect_b32 s45, s27, s64
	s_cselect_b32 s44, s62, s63
	s_add_u32 s100, s46, 0x80
	s_addc_u32 s101, s47, 0
	s_add_i32 m0, s10, 0xc000
	ds_read_b128 v[188:191], v155
	ds_read_b128 v[192:195], v155 offset:1024
	ds_read_b128 v[196:199], v155 offset:2048
	ds_read_b128 v[200:203], v155 offset:3072
	ds_read_b128 v[204:207], v155 offset:4096
	ds_read_b128 v[208:211], v155 offset:5120
	ds_read_b128 v[212:215], v155 offset:6144
	ds_read_b128 v[216:219], v155 offset:7168
	global_load_lds_dwordx4 v136, s[42:43]
	s_add_i32 m0, s10, 0xe000
	s_nop 0
	global_load_lds_dwordx4 v138, s[42:43]
	s_waitcnt vmcnt(8)
	s_waitcnt lgkmcnt(0)
	s_barrier
	s_setprio 2
	s_waitcnt lgkmcnt(0)
	v_mfma_f32_16x16x32_bf16 v[124:127], v[144:147], v[188:191], v[124:127]
	v_mfma_f32_16x16x32_bf16 v[120:123], v[162:165], v[188:191], v[120:123]
	v_mfma_f32_16x16x32_bf16 v[108:111], v[144:147], v[196:199], v[108:111]
	v_mfma_f32_16x16x32_bf16 v[104:107], v[162:165], v[196:199], v[104:107]
	v_mfma_f32_16x16x32_bf16 v[92:95], v[144:147], v[204:207], v[92:95]
	v_mfma_f32_16x16x32_bf16 v[88:91], v[162:165], v[204:207], v[88:91]
	v_mfma_f32_16x16x32_bf16 v[76:79], v[144:147], v[212:215], v[76:79]
	v_mfma_f32_16x16x32_bf16 v[72:75], v[162:165], v[212:215], v[72:75]
	v_mfma_f32_16x16x32_bf16 v[124:127], v[158:161], v[192:195], v[124:127]
	v_mfma_f32_16x16x32_bf16 v[120:123], v[166:169], v[192:195], v[120:123]
	v_mfma_f32_16x16x32_bf16 v[108:111], v[158:161], v[200:203], v[108:111]
	v_mfma_f32_16x16x32_bf16 v[104:107], v[166:169], v[200:203], v[104:107]
	v_mfma_f32_16x16x32_bf16 v[92:95], v[158:161], v[208:211], v[92:95]
	v_mfma_f32_16x16x32_bf16 v[88:91], v[166:169], v[208:211], v[88:91]
	v_mfma_f32_16x16x32_bf16 v[76:79], v[158:161], v[216:219], v[76:79]
	v_mfma_f32_16x16x32_bf16 v[72:75], v[166:169], v[216:219], v[72:75]
	s_setprio 0
	s_setprio 2
	v_mfma_f32_16x16x32_bf16 v[116:119], v[170:173], v[188:191], v[116:119]
	v_mfma_f32_16x16x32_bf16 v[112:115], v[180:183], v[188:191], v[112:115]
	v_mfma_f32_16x16x32_bf16 v[100:103], v[170:173], v[196:199], v[100:103]
	v_mfma_f32_16x16x32_bf16 v[96:99], v[180:183], v[196:199], v[96:99]
	v_mfma_f32_16x16x32_bf16 v[84:87], v[170:173], v[204:207], v[84:87]
	v_mfma_f32_16x16x32_bf16 v[80:83], v[180:183], v[204:207], v[80:83]
	v_mfma_f32_16x16x32_bf16 v[68:71], v[170:173], v[212:215], v[68:71]
	v_mfma_f32_16x16x32_bf16 v[64:67], v[180:183], v[212:215], v[64:67]
	v_mfma_f32_16x16x32_bf16 v[116:119], v[176:179], v[192:195], v[116:119]
	v_mfma_f32_16x16x32_bf16 v[112:115], v[184:187], v[192:195], v[112:115]
	v_mfma_f32_16x16x32_bf16 v[100:103], v[176:179], v[200:203], v[100:103]
	v_mfma_f32_16x16x32_bf16 v[96:99], v[184:187], v[200:203], v[96:99]
	v_mfma_f32_16x16x32_bf16 v[84:87], v[176:179], v[208:211], v[84:87]
	v_mfma_f32_16x16x32_bf16 v[80:83], v[184:187], v[208:211], v[80:83]
	v_mfma_f32_16x16x32_bf16 v[68:71], v[176:179], v[216:219], v[68:71]
	v_mfma_f32_16x16x32_bf16 v[64:67], v[184:187], v[216:219], v[64:67]
	s_setprio 0
	s_add_i32 s66, s49, s0
	s_mov_b32 m0, s66
	ds_read_b128 v[188:191], v155 offset:16384
	ds_read_b128 v[192:195], v155 offset:17408
	ds_read_b128 v[196:199], v155 offset:18432
	ds_read_b128 v[200:203], v155 offset:19456
	ds_read_b128 v[204:207], v155 offset:20480
	ds_read_b128 v[208:211], v155 offset:21504
	ds_read_b128 v[212:215], v155 offset:22528
	ds_read_b128 v[216:219], v155 offset:23552
	global_load_lds_dwordx4 v132, s[44:45]
	s_add_i32 m0, s66, 0x2000
	s_add_u32 s66, s44, 0x80000
	s_addc_u32 s67, s45, 0
	s_add_i32 s68, s50, s0
	global_load_lds_dwordx4 v128, s[44:45]
	s_mov_b32 m0, s68
	s_nop 0
	global_load_lds_dwordx4 v132, s[66:67]
	s_add_i32 m0, s68, 0x2000
	s_nop 0
	global_load_lds_dwordx4 v128, s[66:67]
	s_mov_b32 m0, s10
	s_nop 0
	global_load_lds_dwordx4 v134, s[46:47]
	s_mov_b32 m0, s11
	s_nop 0
	global_load_lds_dwordx4 v130, s[46:47]
	s_waitcnt vmcnt(8)
	s_waitcnt lgkmcnt(0)
	s_barrier
	s_setprio 2
	s_waitcnt lgkmcnt(0)
	v_mfma_f32_16x16x32_bf16 v[60:63], v[144:147], v[188:191], v[60:63]
	v_mfma_f32_16x16x32_bf16 v[56:59], v[162:165], v[188:191], v[56:59]
	v_mfma_f32_16x16x32_bf16 v[44:47], v[144:147], v[196:199], v[44:47]
	v_mfma_f32_16x16x32_bf16 v[40:43], v[162:165], v[196:199], v[40:43]
	v_mfma_f32_16x16x32_bf16 v[28:31], v[144:147], v[204:207], v[28:31]
	v_mfma_f32_16x16x32_bf16 v[24:27], v[162:165], v[204:207], v[24:27]
	v_mfma_f32_16x16x32_bf16 v[12:15], v[144:147], v[212:215], v[12:15]
	v_mfma_f32_16x16x32_bf16 v[8:11], v[162:165], v[212:215], v[8:11]
	v_mfma_f32_16x16x32_bf16 v[60:63], v[158:161], v[192:195], v[60:63]
	v_mfma_f32_16x16x32_bf16 v[56:59], v[166:169], v[192:195], v[56:59]
	v_mfma_f32_16x16x32_bf16 v[44:47], v[158:161], v[200:203], v[44:47]
	v_mfma_f32_16x16x32_bf16 v[40:43], v[166:169], v[200:203], v[40:43]
	v_mfma_f32_16x16x32_bf16 v[28:31], v[158:161], v[208:211], v[28:31]
	v_mfma_f32_16x16x32_bf16 v[24:27], v[166:169], v[208:211], v[24:27]
	v_mfma_f32_16x16x32_bf16 v[12:15], v[158:161], v[216:219], v[12:15]
	v_mfma_f32_16x16x32_bf16 v[8:11], v[166:169], v[216:219], v[8:11]
	s_setprio 0
	s_setprio 2
	v_mfma_f32_16x16x32_bf16 v[52:55], v[170:173], v[188:191], v[52:55]
	v_mfma_f32_16x16x32_bf16 v[48:51], v[180:183], v[188:191], v[48:51]
	v_mfma_f32_16x16x32_bf16 v[36:39], v[170:173], v[196:199], v[36:39]
	v_mfma_f32_16x16x32_bf16 v[32:35], v[180:183], v[196:199], v[32:35]
	v_mfma_f32_16x16x32_bf16 v[20:23], v[170:173], v[204:207], v[20:23]
	v_mfma_f32_16x16x32_bf16 v[16:19], v[180:183], v[204:207], v[16:19]
	v_mfma_f32_16x16x32_bf16 v[4:7], v[170:173], v[212:215], v[4:7]
	v_mfma_f32_16x16x32_bf16 v[0:3], v[180:183], v[212:215], v[0:3]
	v_mfma_f32_16x16x32_bf16 v[52:55], v[176:179], v[192:195], v[52:55]
	v_mfma_f32_16x16x32_bf16 v[48:51], v[184:187], v[192:195], v[48:51]
	v_mfma_f32_16x16x32_bf16 v[36:39], v[176:179], v[200:203], v[36:39]
	v_mfma_f32_16x16x32_bf16 v[32:35], v[184:187], v[200:203], v[32:35]
	v_mfma_f32_16x16x32_bf16 v[20:23], v[176:179], v[208:211], v[20:23]
	v_mfma_f32_16x16x32_bf16 v[16:19], v[184:187], v[208:211], v[16:19]
	v_mfma_f32_16x16x32_bf16 v[4:7], v[176:179], v[216:219], v[4:7]
	v_mfma_f32_16x16x32_bf16 v[0:3], v[184:187], v[216:219], v[0:3]
	s_setprio 0
	s_add_i32 s66, 0, 0x18000
	v_add_u32_e32 v157, s66, v151
	s_add_i32 s67, 0, 0x1c000
	ds_read_b128 v[144:147], v157
	ds_read_b128 v[158:161], v157 offset:1024
	ds_read_b128 v[162:165], v157 offset:2048
	ds_read_b128 v[166:169], v157 offset:3072
	v_add_u32_e32 v157, s67, v151
	ds_read_b128 v[170:173], v157
	ds_read_b128 v[176:179], v157 offset:1024
	ds_read_b128 v[180:183], v157 offset:2048
	ds_read_b128 v[184:187], v157 offset:3072
	s_add_u32 s46, s46, 0x80000
	s_addc_u32 s47, s47, 0
	s_mov_b32 m0, s14
	ds_read_b128 v[188:191], v155 offset:32768
	ds_read_b128 v[192:195], v155 offset:33792
	ds_read_b128 v[196:199], v155 offset:34816
	ds_read_b128 v[200:203], v155 offset:35840
	ds_read_b128 v[204:207], v155 offset:36864
	ds_read_b128 v[208:211], v155 offset:37888
	ds_read_b128 v[212:215], v155 offset:38912
	ds_read_b128 v[216:219], v155 offset:39936
	global_load_lds_dwordx4 v134, s[46:47]
	s_mov_b32 m0, s15
	s_nop 0
	global_load_lds_dwordx4 v130, s[46:47]
	s_waitcnt vmcnt(8)
	s_waitcnt lgkmcnt(0)
	s_barrier
	s_setprio 2
	s_waitcnt lgkmcnt(0)
	v_mfma_f32_16x16x32_bf16 v[124:127], v[144:147], v[188:191], v[124:127]
	v_mfma_f32_16x16x32_bf16 v[120:123], v[162:165], v[188:191], v[120:123]
	v_mfma_f32_16x16x32_bf16 v[108:111], v[144:147], v[196:199], v[108:111]
	v_mfma_f32_16x16x32_bf16 v[104:107], v[162:165], v[196:199], v[104:107]
	v_mfma_f32_16x16x32_bf16 v[92:95], v[144:147], v[204:207], v[92:95]
	v_mfma_f32_16x16x32_bf16 v[88:91], v[162:165], v[204:207], v[88:91]
	v_mfma_f32_16x16x32_bf16 v[76:79], v[144:147], v[212:215], v[76:79]
	v_mfma_f32_16x16x32_bf16 v[72:75], v[162:165], v[212:215], v[72:75]
	v_mfma_f32_16x16x32_bf16 v[124:127], v[158:161], v[192:195], v[124:127]
	v_mfma_f32_16x16x32_bf16 v[120:123], v[166:169], v[192:195], v[120:123]
	v_mfma_f32_16x16x32_bf16 v[108:111], v[158:161], v[200:203], v[108:111]
	v_mfma_f32_16x16x32_bf16 v[104:107], v[166:169], v[200:203], v[104:107]
	v_mfma_f32_16x16x32_bf16 v[92:95], v[158:161], v[208:211], v[92:95]
	v_mfma_f32_16x16x32_bf16 v[88:91], v[166:169], v[208:211], v[88:91]
	v_mfma_f32_16x16x32_bf16 v[76:79], v[158:161], v[216:219], v[76:79]
	v_mfma_f32_16x16x32_bf16 v[72:75], v[166:169], v[216:219], v[72:75]
	s_setprio 0
	s_setprio 2
	v_mfma_f32_16x16x32_bf16 v[116:119], v[170:173], v[188:191], v[116:119]
	v_mfma_f32_16x16x32_bf16 v[112:115], v[180:183], v[188:191], v[112:115]
	v_mfma_f32_16x16x32_bf16 v[100:103], v[170:173], v[196:199], v[100:103]
	v_mfma_f32_16x16x32_bf16 v[96:99], v[180:183], v[196:199], v[96:99]
	v_mfma_f32_16x16x32_bf16 v[84:87], v[170:173], v[204:207], v[84:87]
	v_mfma_f32_16x16x32_bf16 v[80:83], v[180:183], v[204:207], v[80:83]
	v_mfma_f32_16x16x32_bf16 v[68:71], v[170:173], v[212:215], v[68:71]
	v_mfma_f32_16x16x32_bf16 v[64:67], v[180:183], v[212:215], v[64:67]
	v_mfma_f32_16x16x32_bf16 v[116:119], v[176:179], v[192:195], v[116:119]
	v_mfma_f32_16x16x32_bf16 v[112:115], v[184:187], v[192:195], v[112:115]
	v_mfma_f32_16x16x32_bf16 v[100:103], v[176:179], v[200:203], v[100:103]
	v_mfma_f32_16x16x32_bf16 v[96:99], v[184:187], v[200:203], v[96:99]
	v_mfma_f32_16x16x32_bf16 v[84:87], v[176:179], v[208:211], v[84:87]
	v_mfma_f32_16x16x32_bf16 v[80:83], v[184:187], v[208:211], v[80:83]
	v_mfma_f32_16x16x32_bf16 v[68:71], v[176:179], v[216:219], v[68:71]
	v_mfma_f32_16x16x32_bf16 v[64:67], v[184:187], v[216:219], v[64:67]
	s_setprio 0
	s_add_i32 s46, s66, s0
	s_add_u32 s98, s44, 0x80
	s_addc_u32 s99, s45, 0
	s_mov_b32 m0, s46
	ds_read_b128 v[188:191], v155 offset:49152
	ds_read_b128 v[192:195], v155 offset:50176
	ds_read_b128 v[196:199], v155 offset:51200
	ds_read_b128 v[200:203], v155 offset:52224
	ds_read_b128 v[204:207], v155 offset:53248
	ds_read_b128 v[208:211], v155 offset:54272
	ds_read_b128 v[212:215], v155 offset:55296
	ds_read_b128 v[216:219], v155 offset:56320
	global_load_lds_dwordx4 v132, s[98:99]
	s_add_i32 m0, s46, 0x2000
	s_add_u32 s44, s44, 0x80080
	s_addc_u32 s45, s45, 0
	s_add_i32 s46, s67, s0
	global_load_lds_dwordx4 v128, s[98:99]
	s_mov_b32 m0, s46
	s_nop 0
	global_load_lds_dwordx4 v132, s[44:45]
	s_add_i32 m0, s46, 0x2000
	s_nop 0
	global_load_lds_dwordx4 v128, s[44:45]
	s_mov_b32 m0, s41
	s_nop 0
	global_load_lds_dwordx4 v134, s[100:101]
	s_mov_b32 m0, s48
	s_nop 0
	global_load_lds_dwordx4 v130, s[100:101]
	s_waitcnt vmcnt(8)
	s_waitcnt lgkmcnt(0)
	s_barrier
	s_setprio 2
	s_waitcnt lgkmcnt(0)
	v_mfma_f32_16x16x32_bf16 v[60:63], v[144:147], v[188:191], v[60:63]
	v_mfma_f32_16x16x32_bf16 v[56:59], v[162:165], v[188:191], v[56:59]
	v_mfma_f32_16x16x32_bf16 v[44:47], v[144:147], v[196:199], v[44:47]
	v_mfma_f32_16x16x32_bf16 v[40:43], v[162:165], v[196:199], v[40:43]
	v_mfma_f32_16x16x32_bf16 v[28:31], v[144:147], v[204:207], v[28:31]
	v_mfma_f32_16x16x32_bf16 v[24:27], v[162:165], v[204:207], v[24:27]
	v_mfma_f32_16x16x32_bf16 v[12:15], v[144:147], v[212:215], v[12:15]
	v_mfma_f32_16x16x32_bf16 v[8:11], v[162:165], v[212:215], v[8:11]
	v_mfma_f32_16x16x32_bf16 v[60:63], v[158:161], v[192:195], v[60:63]
	v_mfma_f32_16x16x32_bf16 v[56:59], v[166:169], v[192:195], v[56:59]
	v_mfma_f32_16x16x32_bf16 v[44:47], v[158:161], v[200:203], v[44:47]
	v_mfma_f32_16x16x32_bf16 v[40:43], v[166:169], v[200:203], v[40:43]
	v_mfma_f32_16x16x32_bf16 v[28:31], v[158:161], v[208:211], v[28:31]
	v_mfma_f32_16x16x32_bf16 v[24:27], v[166:169], v[208:211], v[24:27]
	v_mfma_f32_16x16x32_bf16 v[12:15], v[158:161], v[216:219], v[12:15]
	v_mfma_f32_16x16x32_bf16 v[8:11], v[166:169], v[216:219], v[8:11]
	s_setprio 0
	s_setprio 2
	v_mfma_f32_16x16x32_bf16 v[52:55], v[170:173], v[188:191], v[52:55]
	v_mfma_f32_16x16x32_bf16 v[48:51], v[180:183], v[188:191], v[48:51]
	v_mfma_f32_16x16x32_bf16 v[36:39], v[170:173], v[196:199], v[36:39]
	v_mfma_f32_16x16x32_bf16 v[32:35], v[180:183], v[196:199], v[32:35]
	v_mfma_f32_16x16x32_bf16 v[20:23], v[170:173], v[204:207], v[20:23]
	v_mfma_f32_16x16x32_bf16 v[16:19], v[180:183], v[204:207], v[16:19]
	v_mfma_f32_16x16x32_bf16 v[4:7], v[170:173], v[212:215], v[4:7]
	v_mfma_f32_16x16x32_bf16 v[0:3], v[180:183], v[212:215], v[0:3]
	v_mfma_f32_16x16x32_bf16 v[52:55], v[176:179], v[192:195], v[52:55]
	v_mfma_f32_16x16x32_bf16 v[48:51], v[184:187], v[192:195], v[48:51]
	v_mfma_f32_16x16x32_bf16 v[36:39], v[176:179], v[200:203], v[36:39]
	v_mfma_f32_16x16x32_bf16 v[32:35], v[184:187], v[200:203], v[32:35]
	v_mfma_f32_16x16x32_bf16 v[20:23], v[176:179], v[208:211], v[20:23]
	v_mfma_f32_16x16x32_bf16 v[16:19], v[184:187], v[208:211], v[16:19]
	v_mfma_f32_16x16x32_bf16 v[4:7], v[176:179], v[216:219], v[4:7]
	v_mfma_f32_16x16x32_bf16 v[0:3], v[184:187], v[216:219], v[0:3]
	s_setprio 0
	s_add_i32 s65, s65, 2
	s_add_u32 s42, s42, 0x100
	s_addc_u32 s43, s43, 0
	s_add_u32 s63, s63, 0x100
	s_addc_u32 s64, s64, 0
	s_cmp_gt_u32 s65, 29
	s_cbranch_scc0 .Lp7_kloop_h1
.Lp7_kloop_done:
.LBB0_796:
	s_andn2_b64 vcc, exec, s[4:5]
	s_mov_b64 s[4:5], -1
	v_lshl_add_u32 v148, s40, 8, v150
	v_add_u32_e32 v160, 64, v148
	v_lshl_or_b32 v146, s60, 7, v152
	v_ashrrev_i32_e32 v161, 31, v160
	v_mov_b64_e32 v[144:145], s[12:13]
	v_lshlrev_b64 v[158:159], 5, v[160:161]
	v_ashrrev_i32_e32 v147, 31, v146
	v_lshl_add_u64 v[158:159], s[22:23], 0, v[158:159]
	global_load_dwordx4 v[176:179], v[158:159], off offset:-2048
	global_load_dwordx4 v[180:183], v[158:159], off offset:-2032
	global_load_dwordx4 v[184:187], v[158:159], off offset:-1536
	global_load_dwordx4 v[188:191], v[158:159], off offset:-1520
	global_load_dwordx4 v[192:195], v[158:159], off offset:-1024
	global_load_dwordx4 v[196:199], v[158:159], off offset:-1008
	global_load_dwordx4 v[200:203], v[158:159], off offset:-512
	global_load_dwordx4 v[204:207], v[158:159], off offset:-496
	global_load_dwordx4 v[208:211], v[158:159], off offset:2048
	global_load_dwordx4 v[212:215], v[158:159], off offset:2064
	global_load_dwordx4 v[216:219], v[158:159], off offset:2560
	global_load_dwordx4 v[220:223], v[158:159], off offset:2576
	global_load_dwordx4 v[224:227], v[158:159], off offset:3072
	global_load_dwordx4 v[228:231], v[158:159], off offset:3088
	global_load_dwordx4 v[232:235], v[158:159], off offset:3584
	global_load_dwordx4 v[236:239], v[158:159], off offset:3600
	v_mad_i64_i32 v[160:161], s[42:43], v148, s51, v[144:145]
	v_lshlrev_b64 v[146:147], 1, v[146:147]
	s_mov_b32 s66, 0x2c000
	s_mov_b32 s67, 0
	v_lshl_add_u64 v[160:161], v[160:161], 0, v[146:147]
	s_waitcnt vmcnt(14)
	v_add_f32_e32 v176, v176, v177
	v_add_f32_e32 v178, v178, v179
	v_add_f32_e32 v180, v180, v181
	v_add_f32_e32 v182, v182, v183
	v_add_f32_e32 v176, v176, v178
	v_add_f32_e32 v180, v180, v182
	v_add_f32_e32 v176, v176, v180
	v_fmamk_f32 v177, v176, 0x3a000000, v156
	v_rsq_f32_e32 v178, v177
	v_pk_mul_f32 v[116:117], v[124:125], v[116:117]
	v_pk_mul_f32 v[118:119], v[126:127], v[118:119]
	v_pk_mul_f32 v[112:113], v[120:121], v[112:113]
	v_pk_mul_f32 v[114:115], v[122:123], v[114:115]
	v_mul_f32_e32 v179, 0xbfb8aa3b, v178
	v_mul_f32_e32 v162, v179, v124
	v_mul_f32_e32 v163, v179, v125
	v_mul_f32_e32 v164, v179, v126
	v_mul_f32_e32 v165, v179, v127
	v_mul_f32_e32 v166, v179, v120
	v_mul_f32_e32 v167, v179, v121
	v_mul_f32_e32 v168, v179, v122
	v_mul_f32_e32 v169, v179, v123
	v_exp_f32_e32 v162, v162
	v_exp_f32_e32 v163, v163
	v_exp_f32_e32 v164, v164
	v_exp_f32_e32 v165, v165
	v_exp_f32_e32 v166, v166
	v_exp_f32_e32 v167, v167
	v_exp_f32_e32 v168, v168
	v_exp_f32_e32 v169, v169
	v_fma_f32 v162, v162, v177, v177
	v_fma_f32 v163, v163, v177, v177
	v_fma_f32 v164, v164, v177, v177
	v_fma_f32 v165, v165, v177, v177
	v_fma_f32 v166, v166, v177, v177
	v_fma_f32 v167, v167, v177, v177
	v_fma_f32 v168, v168, v177, v177
	v_fma_f32 v169, v169, v177, v177
	v_rcp_f32_e32 v162, v162
	v_rcp_f32_e32 v163, v163
	v_rcp_f32_e32 v164, v164
	v_rcp_f32_e32 v165, v165
	v_rcp_f32_e32 v166, v166
	v_rcp_f32_e32 v167, v167
	v_rcp_f32_e32 v168, v168
	v_rcp_f32_e32 v169, v169
	v_pk_mul_f32 v[116:117], v[116:117], v[162:163]
	v_pk_mul_f32 v[118:119], v[118:119], v[164:165]
	v_pk_mul_f32 v[112:113], v[112:113], v[166:167]
	v_pk_mul_f32 v[114:115], v[114:115], v[168:169]
	v_cvt_pk_bf16_f32 v170, v116, v117
	v_cvt_pk_bf16_f32 v171, v118, v119
	v_cvt_pk_bf16_f32 v172, v112, v113
	v_cvt_pk_bf16_f32 v173, v114, v115
	global_store_dwordx4 v[160:161], v[170:173], off
	v_lshl_add_u64 v[160:161], v[160:161], 0, s[66:67]
	s_waitcnt vmcnt(13)
	v_add_f32_e32 v184, v184, v185
	v_add_f32_e32 v186, v186, v187
	v_add_f32_e32 v188, v188, v189
	v_add_f32_e32 v190, v190, v191
	v_add_f32_e32 v184, v184, v186
	v_add_f32_e32 v188, v188, v190
	v_add_f32_e32 v184, v184, v188
	v_fmamk_f32 v185, v184, 0x3a000000, v156
	v_rsq_f32_e32 v186, v185
	v_pk_mul_f32 v[100:101], v[108:109], v[100:101]
	v_pk_mul_f32 v[102:103], v[110:111], v[102:103]
	v_pk_mul_f32 v[96:97], v[104:105], v[96:97]
	v_pk_mul_f32 v[98:99], v[106:107], v[98:99]
	v_mul_f32_e32 v187, 0xbfb8aa3b, v186
	v_mul_f32_e32 v162, v187, v108
	v_mul_f32_e32 v163, v187, v109
	v_mul_f32_e32 v164, v187, v110
	v_mul_f32_e32 v165, v187, v111
	v_mul_f32_e32 v166, v187, v104
	v_mul_f32_e32 v167, v187, v105
	v_mul_f32_e32 v168, v187, v106
	v_mul_f32_e32 v169, v187, v107
	v_exp_f32_e32 v162, v162
	v_exp_f32_e32 v163, v163
	v_exp_f32_e32 v164, v164
	v_exp_f32_e32 v165, v165
	v_exp_f32_e32 v166, v166
	v_exp_f32_e32 v167, v167
	v_exp_f32_e32 v168, v168
	v_exp_f32_e32 v169, v169
	v_fma_f32 v162, v162, v185, v185
	v_fma_f32 v163, v163, v185, v185
	v_fma_f32 v164, v164, v185, v185
	v_fma_f32 v165, v165, v185, v185
	v_fma_f32 v166, v166, v185, v185
	v_fma_f32 v167, v167, v185, v185
	v_fma_f32 v168, v168, v185, v185
	v_fma_f32 v169, v169, v185, v185
	v_rcp_f32_e32 v162, v162
	v_rcp_f32_e32 v163, v163
	v_rcp_f32_e32 v164, v164
	v_rcp_f32_e32 v165, v165
	v_rcp_f32_e32 v166, v166
	v_rcp_f32_e32 v167, v167
	v_rcp_f32_e32 v168, v168
	v_rcp_f32_e32 v169, v169
	v_pk_mul_f32 v[100:101], v[100:101], v[162:163]
	v_pk_mul_f32 v[102:103], v[102:103], v[164:165]
	v_pk_mul_f32 v[96:97], v[96:97], v[166:167]
	v_pk_mul_f32 v[98:99], v[98:99], v[168:169]
	v_cvt_pk_bf16_f32 v170, v100, v101
	v_cvt_pk_bf16_f32 v171, v102, v103
	v_cvt_pk_bf16_f32 v172, v96, v97
	v_cvt_pk_bf16_f32 v173, v98, v99
	global_store_dwordx4 v[160:161], v[170:173], off
	v_lshl_add_u64 v[160:161], v[160:161], 0, s[66:67]
	s_waitcnt vmcnt(12)
	v_add_f32_e32 v192, v192, v193
	v_add_f32_e32 v194, v194, v195
	v_add_f32_e32 v196, v196, v197
	v_add_f32_e32 v198, v198, v199
	v_add_f32_e32 v192, v192, v194
	v_add_f32_e32 v196, v196, v198
	v_add_f32_e32 v192, v192, v196
	v_fmamk_f32 v193, v192, 0x3a000000, v156
	v_rsq_f32_e32 v194, v193
	v_pk_mul_f32 v[84:85], v[92:93], v[84:85]
	v_pk_mul_f32 v[86:87], v[94:95], v[86:87]
	v_pk_mul_f32 v[80:81], v[88:89], v[80:81]
	v_pk_mul_f32 v[82:83], v[90:91], v[82:83]
	v_mul_f32_e32 v195, 0xbfb8aa3b, v194
	v_mul_f32_e32 v162, v195, v92
	v_mul_f32_e32 v163, v195, v93
	v_mul_f32_e32 v164, v195, v94
	v_mul_f32_e32 v165, v195, v95
	v_mul_f32_e32 v166, v195, v88
	v_mul_f32_e32 v167, v195, v89
	v_mul_f32_e32 v168, v195, v90
	v_mul_f32_e32 v169, v195, v91
	v_exp_f32_e32 v162, v162
	v_exp_f32_e32 v163, v163
	v_exp_f32_e32 v164, v164
	v_exp_f32_e32 v165, v165
	v_exp_f32_e32 v166, v166
	v_exp_f32_e32 v167, v167
	v_exp_f32_e32 v168, v168
	v_exp_f32_e32 v169, v169
	v_fma_f32 v162, v162, v193, v193
	v_fma_f32 v163, v163, v193, v193
	v_fma_f32 v164, v164, v193, v193
	v_fma_f32 v165, v165, v193, v193
	v_fma_f32 v166, v166, v193, v193
	v_fma_f32 v167, v167, v193, v193
	v_fma_f32 v168, v168, v193, v193
	v_fma_f32 v169, v169, v193, v193
	v_rcp_f32_e32 v162, v162
	v_rcp_f32_e32 v163, v163
	v_rcp_f32_e32 v164, v164
	v_rcp_f32_e32 v165, v165
	v_rcp_f32_e32 v166, v166
	v_rcp_f32_e32 v167, v167
	v_rcp_f32_e32 v168, v168
	v_rcp_f32_e32 v169, v169
	v_pk_mul_f32 v[84:85], v[84:85], v[162:163]
	v_pk_mul_f32 v[86:87], v[86:87], v[164:165]
	v_pk_mul_f32 v[80:81], v[80:81], v[166:167]
	v_pk_mul_f32 v[82:83], v[82:83], v[168:169]
	v_cvt_pk_bf16_f32 v170, v84, v85
	v_cvt_pk_bf16_f32 v171, v86, v87
	v_cvt_pk_bf16_f32 v172, v80, v81
	v_cvt_pk_bf16_f32 v173, v82, v83
	global_store_dwordx4 v[160:161], v[170:173], off
	v_lshl_add_u64 v[160:161], v[160:161], 0, s[66:67]
	s_waitcnt vmcnt(11)
	v_add_f32_e32 v200, v200, v201
	v_add_f32_e32 v202, v202, v203
	v_add_f32_e32 v204, v204, v205
	v_add_f32_e32 v206, v206, v207
	v_add_f32_e32 v200, v200, v202
	v_add_f32_e32 v204, v204, v206
	v_add_f32_e32 v200, v200, v204
	v_fmamk_f32 v201, v200, 0x3a000000, v156
	v_rsq_f32_e32 v202, v201
	v_pk_mul_f32 v[68:69], v[76:77], v[68:69]
	v_pk_mul_f32 v[70:71], v[78:79], v[70:71]
	v_pk_mul_f32 v[64:65], v[72:73], v[64:65]
	v_pk_mul_f32 v[66:67], v[74:75], v[66:67]
	v_mul_f32_e32 v203, 0xbfb8aa3b, v202
	v_mul_f32_e32 v162, v203, v76
	v_mul_f32_e32 v163, v203, v77
	v_mul_f32_e32 v164, v203, v78
	v_mul_f32_e32 v165, v203, v79
	v_mul_f32_e32 v166, v203, v72
	v_mul_f32_e32 v167, v203, v73
	v_mul_f32_e32 v168, v203, v74
	v_mul_f32_e32 v169, v203, v75
	v_exp_f32_e32 v162, v162
	v_exp_f32_e32 v163, v163
	v_exp_f32_e32 v164, v164
	v_exp_f32_e32 v165, v165
	v_exp_f32_e32 v166, v166
	v_exp_f32_e32 v167, v167
	v_exp_f32_e32 v168, v168
	v_exp_f32_e32 v169, v169
	v_fma_f32 v162, v162, v201, v201
	v_fma_f32 v163, v163, v201, v201
	v_fma_f32 v164, v164, v201, v201
	v_fma_f32 v165, v165, v201, v201
	v_fma_f32 v166, v166, v201, v201
	v_fma_f32 v167, v167, v201, v201
	v_fma_f32 v168, v168, v201, v201
	v_fma_f32 v169, v169, v201, v201
	v_rcp_f32_e32 v162, v162
	v_rcp_f32_e32 v163, v163
	v_rcp_f32_e32 v164, v164
	v_rcp_f32_e32 v165, v165
	v_rcp_f32_e32 v166, v166
	v_rcp_f32_e32 v167, v167
	v_rcp_f32_e32 v168, v168
	v_rcp_f32_e32 v169, v169
	v_pk_mul_f32 v[68:69], v[68:69], v[162:163]
	v_pk_mul_f32 v[70:71], v[70:71], v[164:165]
	v_pk_mul_f32 v[64:65], v[64:65], v[166:167]
	v_pk_mul_f32 v[66:67], v[66:67], v[168:169]
	v_cvt_pk_bf16_f32 v170, v68, v69
	v_cvt_pk_bf16_f32 v171, v70, v71
	v_cvt_pk_bf16_f32 v172, v64, v65
	v_cvt_pk_bf16_f32 v173, v66, v67
	global_store_dwordx4 v[160:161], v[170:173], off
	s_mov_b32 s66, 0xdc000
	v_lshl_add_u64 v[160:161], v[160:161], 0, s[66:67]
	s_waitcnt vmcnt(10)
	v_add_f32_e32 v208, v208, v209
	v_add_f32_e32 v210, v210, v211
	v_add_f32_e32 v212, v212, v213
	v_add_f32_e32 v214, v214, v215
	v_add_f32_e32 v208, v208, v210
	v_add_f32_e32 v212, v212, v214
	v_add_f32_e32 v208, v208, v212
	v_fmamk_f32 v209, v208, 0x3a000000, v156
	v_rsq_f32_e32 v210, v209
	v_pk_mul_f32 v[52:53], v[60:61], v[52:53]
	v_pk_mul_f32 v[54:55], v[62:63], v[54:55]
	v_pk_mul_f32 v[48:49], v[56:57], v[48:49]
	v_pk_mul_f32 v[50:51], v[58:59], v[50:51]
	v_mul_f32_e32 v211, 0xbfb8aa3b, v210
	v_mul_f32_e32 v162, v211, v60
	v_mul_f32_e32 v163, v211, v61
	v_mul_f32_e32 v164, v211, v62
	v_mul_f32_e32 v165, v211, v63
	v_mul_f32_e32 v166, v211, v56
	v_mul_f32_e32 v167, v211, v57
	v_mul_f32_e32 v168, v211, v58
	v_mul_f32_e32 v169, v211, v59
	v_exp_f32_e32 v162, v162
	v_exp_f32_e32 v163, v163
	v_exp_f32_e32 v164, v164
	v_exp_f32_e32 v165, v165
	v_exp_f32_e32 v166, v166
	v_exp_f32_e32 v167, v167
	v_exp_f32_e32 v168, v168
	v_exp_f32_e32 v169, v169
	v_fma_f32 v162, v162, v209, v209
	v_fma_f32 v163, v163, v209, v209
	v_fma_f32 v164, v164, v209, v209
	v_fma_f32 v165, v165, v209, v209
	v_fma_f32 v166, v166, v209, v209
	v_fma_f32 v167, v167, v209, v209
	v_fma_f32 v168, v168, v209, v209
	v_fma_f32 v169, v169, v209, v209
	v_rcp_f32_e32 v162, v162
	v_rcp_f32_e32 v163, v163
	v_rcp_f32_e32 v164, v164
	v_rcp_f32_e32 v165, v165
	v_rcp_f32_e32 v166, v166
	v_rcp_f32_e32 v167, v167
	v_rcp_f32_e32 v168, v168
	v_rcp_f32_e32 v169, v169
	v_pk_mul_f32 v[52:53], v[52:53], v[162:163]
	v_pk_mul_f32 v[54:55], v[54:55], v[164:165]
	v_pk_mul_f32 v[48:49], v[48:49], v[166:167]
	v_pk_mul_f32 v[50:51], v[50:51], v[168:169]
	v_cvt_pk_bf16_f32 v170, v52, v53
	v_cvt_pk_bf16_f32 v171, v54, v55
	v_cvt_pk_bf16_f32 v172, v48, v49
	v_cvt_pk_bf16_f32 v173, v50, v51
	global_store_dwordx4 v[160:161], v[170:173], off
	s_mov_b32 s66, 0x2c000
	v_lshl_add_u64 v[160:161], v[160:161], 0, s[66:67]
	s_waitcnt vmcnt(9)
	v_add_f32_e32 v216, v216, v217
	v_add_f32_e32 v218, v218, v219
	v_add_f32_e32 v220, v220, v221
	v_add_f32_e32 v222, v222, v223
	v_add_f32_e32 v216, v216, v218
	v_add_f32_e32 v220, v220, v222
	v_add_f32_e32 v216, v216, v220
	v_fmamk_f32 v217, v216, 0x3a000000, v156
	v_rsq_f32_e32 v218, v217
	v_pk_mul_f32 v[36:37], v[44:45], v[36:37]
	v_pk_mul_f32 v[38:39], v[46:47], v[38:39]
	v_pk_mul_f32 v[32:33], v[40:41], v[32:33]
	v_pk_mul_f32 v[34:35], v[42:43], v[34:35]
	v_mul_f32_e32 v219, 0xbfb8aa3b, v218
	v_mul_f32_e32 v162, v219, v44
	v_mul_f32_e32 v163, v219, v45
	v_mul_f32_e32 v164, v219, v46
	v_mul_f32_e32 v165, v219, v47
	v_mul_f32_e32 v166, v219, v40
	v_mul_f32_e32 v167, v219, v41
	v_mul_f32_e32 v168, v219, v42
	v_mul_f32_e32 v169, v219, v43
	v_exp_f32_e32 v162, v162
	v_exp_f32_e32 v163, v163
	v_exp_f32_e32 v164, v164
	v_exp_f32_e32 v165, v165
	v_exp_f32_e32 v166, v166
	v_exp_f32_e32 v167, v167
	v_exp_f32_e32 v168, v168
	v_exp_f32_e32 v169, v169
	v_fma_f32 v162, v162, v217, v217
	v_fma_f32 v163, v163, v217, v217
	v_fma_f32 v164, v164, v217, v217
	v_fma_f32 v165, v165, v217, v217
	v_fma_f32 v166, v166, v217, v217
	v_fma_f32 v167, v167, v217, v217
	v_fma_f32 v168, v168, v217, v217
	v_fma_f32 v169, v169, v217, v217
	v_rcp_f32_e32 v162, v162
	v_rcp_f32_e32 v163, v163
	v_rcp_f32_e32 v164, v164
	v_rcp_f32_e32 v165, v165
	v_rcp_f32_e32 v166, v166
	v_rcp_f32_e32 v167, v167
	v_rcp_f32_e32 v168, v168
	v_rcp_f32_e32 v169, v169
	v_pk_mul_f32 v[36:37], v[36:37], v[162:163]
	v_pk_mul_f32 v[38:39], v[38:39], v[164:165]
	v_pk_mul_f32 v[32:33], v[32:33], v[166:167]
	v_pk_mul_f32 v[34:35], v[34:35], v[168:169]
	v_cvt_pk_bf16_f32 v170, v36, v37
	v_cvt_pk_bf16_f32 v171, v38, v39
	v_cvt_pk_bf16_f32 v172, v32, v33
	v_cvt_pk_bf16_f32 v173, v34, v35
	global_store_dwordx4 v[160:161], v[170:173], off
	v_lshl_add_u64 v[160:161], v[160:161], 0, s[66:67]
	s_waitcnt vmcnt(8)
	v_add_f32_e32 v224, v224, v225
	v_add_f32_e32 v226, v226, v227
	v_add_f32_e32 v228, v228, v229
	v_add_f32_e32 v230, v230, v231
	v_add_f32_e32 v224, v224, v226
	v_add_f32_e32 v228, v228, v230
	v_add_f32_e32 v224, v224, v228
	v_fmamk_f32 v225, v224, 0x3a000000, v156
	v_rsq_f32_e32 v226, v225
	v_pk_mul_f32 v[20:21], v[28:29], v[20:21]
	v_pk_mul_f32 v[22:23], v[30:31], v[22:23]
	v_pk_mul_f32 v[16:17], v[24:25], v[16:17]
	v_pk_mul_f32 v[18:19], v[26:27], v[18:19]
	v_mul_f32_e32 v227, 0xbfb8aa3b, v226
	v_mul_f32_e32 v162, v227, v28
	v_mul_f32_e32 v163, v227, v29
	v_mul_f32_e32 v164, v227, v30
	v_mul_f32_e32 v165, v227, v31
	v_mul_f32_e32 v166, v227, v24
	v_mul_f32_e32 v167, v227, v25
	v_mul_f32_e32 v168, v227, v26
	v_mul_f32_e32 v169, v227, v27
	v_exp_f32_e32 v162, v162
	v_exp_f32_e32 v163, v163
	v_exp_f32_e32 v164, v164
	v_exp_f32_e32 v165, v165
	v_exp_f32_e32 v166, v166
	v_exp_f32_e32 v167, v167
	v_exp_f32_e32 v168, v168
	v_exp_f32_e32 v169, v169
	v_fma_f32 v162, v162, v225, v225
	v_fma_f32 v163, v163, v225, v225
	v_fma_f32 v164, v164, v225, v225
	v_fma_f32 v165, v165, v225, v225
	v_fma_f32 v166, v166, v225, v225
	v_fma_f32 v167, v167, v225, v225
	v_fma_f32 v168, v168, v225, v225
	v_fma_f32 v169, v169, v225, v225
	v_rcp_f32_e32 v162, v162
	v_rcp_f32_e32 v163, v163
	v_rcp_f32_e32 v164, v164
	v_rcp_f32_e32 v165, v165
	v_rcp_f32_e32 v166, v166
	v_rcp_f32_e32 v167, v167
	v_rcp_f32_e32 v168, v168
	v_rcp_f32_e32 v169, v169
	v_pk_mul_f32 v[20:21], v[20:21], v[162:163]
	v_pk_mul_f32 v[22:23], v[22:23], v[164:165]
	v_pk_mul_f32 v[16:17], v[16:17], v[166:167]
	v_pk_mul_f32 v[18:19], v[18:19], v[168:169]
	v_cvt_pk_bf16_f32 v170, v20, v21
	v_cvt_pk_bf16_f32 v171, v22, v23
	v_cvt_pk_bf16_f32 v172, v16, v17
	v_cvt_pk_bf16_f32 v173, v18, v19
	global_store_dwordx4 v[160:161], v[170:173], off
	v_lshl_add_u64 v[160:161], v[160:161], 0, s[66:67]
	s_waitcnt vmcnt(7)
	v_add_f32_e32 v232, v232, v233
	v_add_f32_e32 v234, v234, v235
	v_add_f32_e32 v236, v236, v237
	v_add_f32_e32 v238, v238, v239
	v_add_f32_e32 v232, v232, v234
	v_add_f32_e32 v236, v236, v238
	v_add_f32_e32 v232, v232, v236
	v_fmamk_f32 v233, v232, 0x3a000000, v156
	v_rsq_f32_e32 v234, v233
	v_pk_mul_f32 v[4:5], v[12:13], v[4:5]
	v_pk_mul_f32 v[6:7], v[14:15], v[6:7]
	v_pk_mul_f32 v[0:1], v[8:9], v[0:1]
	v_pk_mul_f32 v[2:3], v[10:11], v[2:3]
	v_mul_f32_e32 v235, 0xbfb8aa3b, v234
	v_mul_f32_e32 v162, v235, v12
	v_mul_f32_e32 v163, v235, v13
	v_mul_f32_e32 v164, v235, v14
	v_mul_f32_e32 v165, v235, v15
	v_mul_f32_e32 v166, v235, v8
	v_mul_f32_e32 v167, v235, v9
	v_mul_f32_e32 v168, v235, v10
	v_mul_f32_e32 v169, v235, v11
	v_exp_f32_e32 v162, v162
	v_exp_f32_e32 v163, v163
	v_exp_f32_e32 v164, v164
	v_exp_f32_e32 v165, v165
	v_exp_f32_e32 v166, v166
	v_exp_f32_e32 v167, v167
	v_exp_f32_e32 v168, v168
	v_exp_f32_e32 v169, v169
	v_fma_f32 v162, v162, v233, v233
	v_fma_f32 v163, v163, v233, v233
	v_fma_f32 v164, v164, v233, v233
	v_fma_f32 v165, v165, v233, v233
	v_fma_f32 v166, v166, v233, v233
	v_fma_f32 v167, v167, v233, v233
	v_fma_f32 v168, v168, v233, v233
	v_fma_f32 v169, v169, v233, v233
	v_rcp_f32_e32 v162, v162
	v_rcp_f32_e32 v163, v163
	v_rcp_f32_e32 v164, v164
	v_rcp_f32_e32 v165, v165
	v_rcp_f32_e32 v166, v166
	v_rcp_f32_e32 v167, v167
	v_rcp_f32_e32 v168, v168
	v_rcp_f32_e32 v169, v169
	v_pk_mul_f32 v[4:5], v[4:5], v[162:163]
	v_pk_mul_f32 v[6:7], v[6:7], v[164:165]
	v_pk_mul_f32 v[0:1], v[0:1], v[166:167]
	v_pk_mul_f32 v[2:3], v[2:3], v[168:169]
	v_cvt_pk_bf16_f32 v170, v4, v5
	v_cvt_pk_bf16_f32 v171, v6, v7
	v_cvt_pk_bf16_f32 v172, v0, v1
	v_cvt_pk_bf16_f32 v173, v2, v3
	global_store_dwordx4 v[160:161], v[170:173], off
	s_cbranch_vccnz .LBB0_789
	s_branch .LBB0_788

	.amdhsa_kernel _Z6mk_fwd4Args
		.amdhsa_group_segment_fixed_size 0
		.amdhsa_private_segment_fixed_size 0
		.amdhsa_kernarg_size 440
		.amdhsa_user_sgpr_count 2
		.amdhsa_user_sgpr_dispatch_ptr 0
		.amdhsa_user_sgpr_queue_ptr 0
		.amdhsa_user_sgpr_kernarg_segment_ptr 1
		.amdhsa_user_sgpr_dispatch_id 0
		.amdhsa_user_sgpr_kernarg_preload_length 0
		.amdhsa_user_sgpr_kernarg_preload_offset 0
		.amdhsa_user_sgpr_private_segment_size 0
		.amdhsa_uses_dynamic_stack 0
		.amdhsa_enable_private_segment 0
		.amdhsa_system_sgpr_workgroup_id_x 1
		.amdhsa_system_sgpr_workgroup_id_y 0
		.amdhsa_system_sgpr_workgroup_id_z 0
		.amdhsa_system_sgpr_workgroup_info 0
		.amdhsa_system_vgpr_workitem_id 2
		.amdhsa_next_free_vgpr 241
		.amdhsa_next_free_sgpr 102
		.amdhsa_accum_offset 244
		.amdhsa_reserve_vcc 1
		.amdhsa_float_round_mode_32 0
		.amdhsa_float_round_mode_16_64 0
		.amdhsa_float_denorm_mode_32 3
		.amdhsa_float_denorm_mode_16_64 3
		.amdhsa_dx10_clamp 1
		.amdhsa_ieee_mode 1
		.amdhsa_fp16_overflow 0
		.amdhsa_tg_split 0
		.amdhsa_exception_fp_ieee_invalid_op 0
		.amdhsa_exception_fp_denorm_src 0
		.amdhsa_exception_fp_ieee_div_zero 0
		.amdhsa_exception_fp_ieee_overflow 0
		.amdhsa_exception_fp_ieee_underflow 0
		.amdhsa_exception_fp_ieee_inexact 0
		.amdhsa_exception_int_div_zero 0
	.end_amdhsa_kernel

amdhsa.kernels:
  - .agpr_count:     0
    .args:
      - .offset:         0
        .size:           184
        .value_kind:     by_value
      - .offset:         184
        .size:           4
        .value_kind:     hidden_block_count_x
      - .offset:         188
        .size:           4
        .value_kind:     hidden_block_count_y
      - .offset:         192
        .size:           4
        .value_kind:     hidden_block_count_z
      - .offset:         196
        .size:           2
        .value_kind:     hidden_group_size_x
      - .offset:         198
        .size:           2
        .value_kind:     hidden_group_size_y
      - .offset:         200
        .size:           2
        .value_kind:     hidden_group_size_z
      - .offset:         202
        .size:           2
        .value_kind:     hidden_remainder_x
      - .offset:         204
        .size:           2
        .value_kind:     hidden_remainder_y
      - .offset:         206
        .size:           2
        .value_kind:     hidden_remainder_z
      - .offset:         224
        .size:           8
        .value_kind:     hidden_global_offset_x
      - .offset:         232
        .size:           8
        .value_kind:     hidden_global_offset_y
      - .offset:         240
        .size:           8
        .value_kind:     hidden_global_offset_z
      - .offset:         248
        .size:           2
        .value_kind:     hidden_grid_dims
      - .offset:         272
        .size:           8
        .value_kind:     hidden_multigrid_sync_arg
      - .offset:         304
        .size:           4
        .value_kind:     hidden_dynamic_lds_size
    .group_segment_fixed_size: 0
    .kernarg_segment_align: 8
    .kernarg_segment_size: 440
    .language:       OpenCL C
    .language_version:
      - 2
      - 0
    .max_flat_workgroup_size: 512
    .name:           _Z6mk_fwd4Args
    .private_segment_fixed_size: 0
    .sgpr_count:     108
    .sgpr_spill_count: 48
    .symbol:         _Z6mk_fwd4Args.kd
    .uniform_work_group_size: 1
    .uses_dynamic_stack: false
    .vgpr_count:     241
    .vgpr_spill_count: 0
    .wavefront_size: 64
